# v41 minus the redundant mid-cluster s_setprio 0/1 pairs in the six GEMM main loops
# speedup vs baseline: 1.0393x; 1.0114x over previous
; #define PG8_STAGE(bufoff, gbase, voff) do { _Pragma("unroll") for (int _i = 0; _i < 2; ++_i) \
;         __builtin_amdgcn_global_load_lds((const unsigned*)((const char*)(gbase) + (voff)[_i]), (LAS unsigned*)(lds + (bufoff) + ldsw + _i * 8192), 16, 0, 0); } while (0)
; #define PG8_LDA(dst, b, h) do { _Pragma("unroll") for (int m = 0; m < 4; ++m) _Pragma("unroll") for (int k = 0; k < 2; ++k) dst[m][k] = *(const LAS bf16x8*)(lds + PG8_SA(b, h) + aoff + m * 2048 + k * 1024); } while (0)
; #define PG8_LDB(dst, b, h) do { _Pragma("unroll") for (int n = 0; n < 2; ++n) _Pragma("unroll") for (int k = 0; k < 2; ++k) dst[n][k] = *(const LAS bf16x8*)(lds + PG8_SB(b, h) + boff + n * 2048 + k * 1024); } while (0)
; #define PG8_MMA(ai, bj, At, Bt) do { __builtin_amdgcn_s_setprio(1); _Pragma("unroll") for (int m = 0; m < 4; ++m) _Pragma("unroll") for (int n = 0; n < 2; ++n) _Pragma("unroll") for (int k = 0; k < 2; ++k) \
;         acc[ai][bj][m][n] = __builtin_amdgcn_mfma_f32_16x16x32_bf16(Bt[n][k], At[m][k], acc[ai][bj][m][n], 0, 0, 0); __builtin_amdgcn_s_setprio(0); } while (0)
; #define PG8_WAIT_V(n) asm volatile("s_waitcnt vmcnt(" #n ")" ::: "memory")
; #define PG8_WAIT_L(n) asm volatile("s_waitcnt lgkmcnt(" #n ")" ::: "memory")
; #define PG8_BAR __builtin_amdgcn_s_barrier()
; #define PG8_SCHED __builtin_amdgcn_sched_barrier(0)
; template <class Epi, class Sched>
; __device__ __forceinline__ void gemm_phase(LAS unsigned char* lds, const int K, const Sched& S, const Epi& E) {
;     ...
;             PG8_LDB(B0, 0, 0); PG8_LDB(B1, 0, 1); PG8_SCHED; PG8_LDA(At, 0, 0); PG8_STAGE(PG8_SA(1, 1), a1 + hstep, voffA);
;             PG8_WAIT_V(8); PG8_WAIT_L(0); PG8_BAR; PG8_MMA(0, 0, At, B0); PG8_MMA(0, 1, At, B1); PG8_BAR; PG8_SCHED;
;             PG8_LDA(At, 0, 1); PG8_STAGE(PG8_SB(0, 0), b2, voffB); PG8_STAGE(PG8_SB(0, 1), b2 + hstep, voffB); PG8_STAGE(PG8_SA(0, 0), a2, voffA);
;             PG8_WAIT_V(8); PG8_WAIT_L(0); PG8_BAR; PG8_MMA(1, 0, At, B0); PG8_MMA(1, 1, At, B1); PG8_BAR; PG8_SCHED;
.LBB0_485:
	ds_read_b128 v[140:143], v147
	ds_read_b128 v[150:153], v147 offset:1024
	ds_read_b128 v[154:157], v147 offset:2048
	ds_read_b128 v[158:161], v147 offset:3072
	ds_read_b128 v[162:165], v148
	ds_read_b128 v[170:173], v148 offset:1024
	ds_read_b128 v[174:177], v148 offset:2048
	ds_read_b128 v[178:181], v148 offset:3072
	s_add_u32 s19, s34, 0xfff80080
	s_addc_u32 s38, s35, -1
	s_cmp_eq_u32 s17, 28
	s_cselect_b32 s41, s23, s38
	s_cselect_b32 s40, s22, s19
	s_cselect_b32 s39, s25, s9
	s_cselect_b32 s38, s24, s8
	s_mov_b32 m0, s50
	v_lshl_add_u64 v[166:167], s[34:35], 0, v[136:137]
	ds_read_b128 v[182:185], v149
	ds_read_b128 v[186:189], v149 offset:1024
	ds_read_b128 v[190:193], v149 offset:2048
	ds_read_b128 v[194:197], v149 offset:3072
	ds_read_b128 v[198:201], v149 offset:4096
	ds_read_b128 v[202:205], v149 offset:5120
	ds_read_b128 v[206:209], v149 offset:6144
	ds_read_b128 v[210:213], v149 offset:7168
	global_load_lds_dwordx4 v[166:167], off
	v_lshl_add_u64 v[166:167], s[34:35], 0, v[138:139]
	s_mov_b32 m0, s51
	s_nop 0
	global_load_lds_dwordx4 v[166:167], off
	s_waitcnt vmcnt(8)
	s_waitcnt lgkmcnt(0)
	s_barrier
	s_setprio 1
	s_waitcnt lgkmcnt(0)
	v_mfma_f32_16x16x32_bf16 v[124:127], v[140:143], v[182:185], v[124:127]
	v_mfma_f32_16x16x32_bf16 v[120:123], v[154:157], v[182:185], v[120:123]
	v_mfma_f32_16x16x32_bf16 v[108:111], v[140:143], v[190:193], v[108:111]
	v_mfma_f32_16x16x32_bf16 v[104:107], v[154:157], v[190:193], v[104:107]
	v_mfma_f32_16x16x32_bf16 v[92:95], v[140:143], v[198:201], v[92:95]
	v_mfma_f32_16x16x32_bf16 v[88:91], v[154:157], v[198:201], v[88:91]
	v_mfma_f32_16x16x32_bf16 v[76:79], v[140:143], v[206:209], v[76:79]
	v_mfma_f32_16x16x32_bf16 v[72:75], v[154:157], v[206:209], v[72:75]
	v_mfma_f32_16x16x32_bf16 v[124:127], v[150:153], v[186:189], v[124:127]
	v_mfma_f32_16x16x32_bf16 v[120:123], v[158:161], v[186:189], v[120:123]
	v_mfma_f32_16x16x32_bf16 v[108:111], v[150:153], v[194:197], v[108:111]
	v_mfma_f32_16x16x32_bf16 v[104:107], v[158:161], v[194:197], v[104:107]
	v_mfma_f32_16x16x32_bf16 v[92:95], v[150:153], v[202:205], v[92:95]
	v_mfma_f32_16x16x32_bf16 v[88:91], v[158:161], v[202:205], v[88:91]
	v_mfma_f32_16x16x32_bf16 v[76:79], v[150:153], v[210:213], v[76:79]
	v_mfma_f32_16x16x32_bf16 v[72:75], v[158:161], v[210:213], v[72:75]
	v_mfma_f32_16x16x32_bf16 v[116:119], v[162:165], v[182:185], v[116:119]
	v_mfma_f32_16x16x32_bf16 v[112:115], v[174:177], v[182:185], v[112:115]
	v_mfma_f32_16x16x32_bf16 v[100:103], v[162:165], v[190:193], v[100:103]
	v_mfma_f32_16x16x32_bf16 v[96:99], v[174:177], v[190:193], v[96:99]
	v_mfma_f32_16x16x32_bf16 v[84:87], v[162:165], v[198:201], v[84:87]
	v_mfma_f32_16x16x32_bf16 v[80:83], v[174:177], v[198:201], v[80:83]
	v_mfma_f32_16x16x32_bf16 v[68:71], v[162:165], v[206:209], v[68:71]
	v_mfma_f32_16x16x32_bf16 v[64:67], v[174:177], v[206:209], v[64:67]
	v_mfma_f32_16x16x32_bf16 v[116:119], v[170:173], v[186:189], v[116:119]
	v_mfma_f32_16x16x32_bf16 v[112:115], v[178:181], v[186:189], v[112:115]
	v_mfma_f32_16x16x32_bf16 v[100:103], v[170:173], v[194:197], v[100:103]
	v_mfma_f32_16x16x32_bf16 v[96:99], v[178:181], v[194:197], v[96:99]
	v_mfma_f32_16x16x32_bf16 v[84:87], v[170:173], v[202:205], v[84:87]
	v_mfma_f32_16x16x32_bf16 v[80:83], v[178:181], v[202:205], v[80:83]
	v_mfma_f32_16x16x32_bf16 v[68:71], v[170:173], v[210:213], v[68:71]
	v_mfma_f32_16x16x32_bf16 v[64:67], v[178:181], v[210:213], v[64:67]
	s_setprio 0
	s_barrier
	s_mov_b32 m0, s68
	v_lshl_add_u64 v[166:167], s[38:39], 0, v[130:131]
	ds_read_b128 v[182:185], v149 offset:16384
	ds_read_b128 v[186:189], v149 offset:17408
	ds_read_b128 v[190:193], v149 offset:18432
	ds_read_b128 v[194:197], v149 offset:19456
	ds_read_b128 v[198:201], v149 offset:20480
	ds_read_b128 v[202:205], v149 offset:21504
	ds_read_b128 v[206:209], v149 offset:22528
	ds_read_b128 v[210:213], v149 offset:23552
	global_load_lds_dwordx4 v[166:167], off
	s_add_i32 m0, s68, 0x2000
	s_add_u32 s70, s38, 0x80000
	v_lshl_add_u64 v[214:215], s[38:39], 0, v[134:135]
	s_addc_u32 s71, s39, 0
	s_add_i32 s19, s48, s36
	global_load_lds_dwordx4 v[214:215], off
	v_lshl_add_u64 v[216:217], s[70:71], 0, v[130:131]
	s_mov_b32 m0, s19
	v_lshl_add_u64 v[218:219], s[40:41], 0, v[132:133]
	global_load_lds_dwordx4 v[216:217], off
	v_lshl_add_u64 v[216:217], s[70:71], 0, v[134:135]
	s_add_i32 m0, s19, 0x2000
	s_nop 0
	global_load_lds_dwordx4 v[216:217], off
	v_lshl_add_u64 v[216:217], s[40:41], 0, v[128:129]
	s_mov_b32 m0, s31
	s_nop 0
	global_load_lds_dwordx4 v[216:217], off
	s_mov_b32 m0, s42
	s_nop 0
	global_load_lds_dwordx4 v[218:219], off
	s_waitcnt vmcnt(8)
	s_waitcnt lgkmcnt(0)
	s_barrier
; #define PG8_STAGE(bufoff, gbase, voff) do { _Pragma("unroll") for (int _i = 0; _i < 2; ++_i) \
;         __builtin_amdgcn_global_load_lds((const unsigned*)((const char*)(gbase) + (voff)[_i]), (LAS unsigned*)(lds + (bufoff) + ldsw + _i * 8192), 16, 0, 0); } while (0)
; #define PG8_LDA(dst, b, h) do { _Pragma("unroll") for (int m = 0; m < 4; ++m) _Pragma("unroll") for (int k = 0; k < 2; ++k) dst[m][k] = *(const LAS bf16x8*)(lds + PG8_SA(b, h) + aoff + m * 2048 + k * 1024); } while (0)
; #define PG8_LDB(dst, b, h) do { _Pragma("unroll") for (int n = 0; n < 2; ++n) _Pragma("unroll") for (int k = 0; k < 2; ++k) dst[n][k] = *(const LAS bf16x8*)(lds + PG8_SB(b, h) + boff + n * 2048 + k * 1024); } while (0)
; #define PG8_MMA(ai, bj, At, Bt) do { __builtin_amdgcn_s_setprio(1); _Pragma("unroll") for (int m = 0; m < 4; ++m) _Pragma("unroll") for (int n = 0; n < 2; ++n) _Pragma("unroll") for (int k = 0; k < 2; ++k) \
;         acc[ai][bj][m][n] = __builtin_amdgcn_mfma_f32_16x16x32_bf16(Bt[n][k], At[m][k], acc[ai][bj][m][n], 0, 0, 0); __builtin_amdgcn_s_setprio(0); } while (0)
; #define PG8_WAIT_V(n) asm volatile("s_waitcnt vmcnt(" #n ")" ::: "memory")
; #define PG8_WAIT_L(n) asm volatile("s_waitcnt lgkmcnt(" #n ")" ::: "memory")
; #define PG8_BAR __builtin_amdgcn_s_barrier()
; #define PG8_SCHED __builtin_amdgcn_sched_barrier(0)
; template <class Epi, class Sched>
; __device__ __forceinline__ void gemm_phase(LAS unsigned char* lds, const int K, const Sched& S, const Epi& E) {
;     ...
;             PG8_WAIT_V(8); PG8_WAIT_L(0); PG8_BAR; PG8_MMA(1, 0, At, B0); PG8_MMA(1, 1, At, B1); PG8_BAR; PG8_SCHED;
;             PG8_LDB(B0, 1, 0); PG8_LDB(B1, 1, 1); PG8_SCHED; PG8_LDA(At, 1, 0); PG8_STAGE(PG8_SA(0, 1), a2 + hstep, voffA);
;             PG8_WAIT_V(8); PG8_WAIT_L(0); PG8_BAR; PG8_MMA(0, 0, At, B0); PG8_MMA(0, 1, At, B1); PG8_BAR; PG8_SCHED;
	s_setprio 1
	s_waitcnt lgkmcnt(0)
	v_mfma_f32_16x16x32_bf16 v[60:63], v[140:143], v[182:185], v[60:63]
	v_mfma_f32_16x16x32_bf16 v[56:59], v[154:157], v[182:185], v[56:59]
	v_mfma_f32_16x16x32_bf16 v[44:47], v[140:143], v[190:193], v[44:47]
	v_mfma_f32_16x16x32_bf16 v[40:43], v[154:157], v[190:193], v[40:43]
	v_mfma_f32_16x16x32_bf16 v[28:31], v[140:143], v[198:201], v[28:31]
	v_mfma_f32_16x16x32_bf16 v[24:27], v[154:157], v[198:201], v[24:27]
	v_mfma_f32_16x16x32_bf16 v[12:15], v[140:143], v[206:209], v[12:15]
	v_mfma_f32_16x16x32_bf16 v[8:11], v[154:157], v[206:209], v[8:11]
	v_mfma_f32_16x16x32_bf16 v[60:63], v[150:153], v[186:189], v[60:63]
	v_mfma_f32_16x16x32_bf16 v[56:59], v[158:161], v[186:189], v[56:59]
	v_mfma_f32_16x16x32_bf16 v[44:47], v[150:153], v[194:197], v[44:47]
	v_mfma_f32_16x16x32_bf16 v[40:43], v[158:161], v[194:197], v[40:43]
	v_mfma_f32_16x16x32_bf16 v[28:31], v[150:153], v[202:205], v[28:31]
	v_mfma_f32_16x16x32_bf16 v[24:27], v[158:161], v[202:205], v[24:27]
	v_mfma_f32_16x16x32_bf16 v[12:15], v[150:153], v[210:213], v[12:15]
	v_mfma_f32_16x16x32_bf16 v[8:11], v[158:161], v[210:213], v[8:11]
	v_mfma_f32_16x16x32_bf16 v[52:55], v[162:165], v[182:185], v[52:55]
	v_mfma_f32_16x16x32_bf16 v[48:51], v[174:177], v[182:185], v[48:51]
	v_mfma_f32_16x16x32_bf16 v[36:39], v[162:165], v[190:193], v[36:39]
	v_mfma_f32_16x16x32_bf16 v[32:35], v[174:177], v[190:193], v[32:35]
	v_mfma_f32_16x16x32_bf16 v[20:23], v[162:165], v[198:201], v[20:23]
	v_mfma_f32_16x16x32_bf16 v[16:19], v[174:177], v[198:201], v[16:19]
	v_mfma_f32_16x16x32_bf16 v[4:7], v[162:165], v[206:209], v[4:7]
	v_mfma_f32_16x16x32_bf16 v[0:3], v[174:177], v[206:209], v[0:3]
	v_mfma_f32_16x16x32_bf16 v[52:55], v[170:173], v[186:189], v[52:55]
	v_mfma_f32_16x16x32_bf16 v[48:51], v[178:181], v[186:189], v[48:51]
	v_mfma_f32_16x16x32_bf16 v[36:39], v[170:173], v[194:197], v[36:39]
	v_mfma_f32_16x16x32_bf16 v[32:35], v[178:181], v[194:197], v[32:35]
	v_mfma_f32_16x16x32_bf16 v[20:23], v[170:173], v[202:205], v[20:23]
	v_mfma_f32_16x16x32_bf16 v[16:19], v[178:181], v[202:205], v[16:19]
	v_mfma_f32_16x16x32_bf16 v[4:7], v[170:173], v[210:213], v[4:7]
	v_mfma_f32_16x16x32_bf16 v[0:3], v[178:181], v[210:213], v[0:3]
	s_setprio 0
	s_barrier
	s_add_i32 s19, 0, 0x18000
	s_add_i32 s70, 0, 0x1c000
	v_add_u32_e32 v158, s19, v145
	v_add_u32_e32 v169, s70, v145
	ds_read_b128 v[140:143], v158
	ds_read_b128 v[150:153], v158 offset:1024
	ds_read_b128 v[154:157], v158 offset:2048
	ds_read_b128 v[158:161], v158 offset:3072
	ds_read_b128 v[162:165], v169
	ds_read_b128 v[170:173], v169 offset:1024
	ds_read_b128 v[174:177], v169 offset:2048
	ds_read_b128 v[178:181], v169 offset:3072
	s_add_u32 s40, s40, 0x80000
	s_addc_u32 s41, s41, 0
	s_mov_b32 m0, s43
	v_lshl_add_u64 v[220:221], s[40:41], 0, v[128:129]
	ds_read_b128 v[182:185], v149 offset:32768
	ds_read_b128 v[186:189], v149 offset:33792
	ds_read_b128 v[190:193], v149 offset:34816
	ds_read_b128 v[194:197], v149 offset:35840
	ds_read_b128 v[198:201], v149 offset:36864
	ds_read_b128 v[202:205], v149 offset:37888
	ds_read_b128 v[206:209], v149 offset:38912
	ds_read_b128 v[210:213], v149 offset:39936
	global_load_lds_dwordx4 v[220:221], off
	v_lshl_add_u64 v[220:221], s[40:41], 0, v[132:133]
	s_mov_b32 m0, s44
	s_nop 0
	global_load_lds_dwordx4 v[220:221], off
	s_waitcnt vmcnt(8)
	s_waitcnt lgkmcnt(0)
	s_barrier
	s_setprio 1
	s_waitcnt lgkmcnt(0)
	v_mfma_f32_16x16x32_bf16 v[124:127], v[140:143], v[182:185], v[124:127]
	v_mfma_f32_16x16x32_bf16 v[120:123], v[154:157], v[182:185], v[120:123]
	v_mfma_f32_16x16x32_bf16 v[108:111], v[140:143], v[190:193], v[108:111]
	v_mfma_f32_16x16x32_bf16 v[104:107], v[154:157], v[190:193], v[104:107]
	v_mfma_f32_16x16x32_bf16 v[92:95], v[140:143], v[198:201], v[92:95]
	v_mfma_f32_16x16x32_bf16 v[88:91], v[154:157], v[198:201], v[88:91]
	v_mfma_f32_16x16x32_bf16 v[76:79], v[140:143], v[206:209], v[76:79]
	v_mfma_f32_16x16x32_bf16 v[72:75], v[154:157], v[206:209], v[72:75]
	v_mfma_f32_16x16x32_bf16 v[124:127], v[150:153], v[186:189], v[124:127]
	v_mfma_f32_16x16x32_bf16 v[120:123], v[158:161], v[186:189], v[120:123]
	v_mfma_f32_16x16x32_bf16 v[108:111], v[150:153], v[194:197], v[108:111]
	v_mfma_f32_16x16x32_bf16 v[104:107], v[158:161], v[194:197], v[104:107]
	v_mfma_f32_16x16x32_bf16 v[92:95], v[150:153], v[202:205], v[92:95]
	v_mfma_f32_16x16x32_bf16 v[88:91], v[158:161], v[202:205], v[88:91]
	v_mfma_f32_16x16x32_bf16 v[76:79], v[150:153], v[210:213], v[76:79]
	v_mfma_f32_16x16x32_bf16 v[72:75], v[158:161], v[210:213], v[72:75]
	v_mfma_f32_16x16x32_bf16 v[116:119], v[162:165], v[182:185], v[116:119]
	v_mfma_f32_16x16x32_bf16 v[112:115], v[174:177], v[182:185], v[112:115]
	v_mfma_f32_16x16x32_bf16 v[100:103], v[162:165], v[190:193], v[100:103]
	v_mfma_f32_16x16x32_bf16 v[96:99], v[174:177], v[190:193], v[96:99]
	v_mfma_f32_16x16x32_bf16 v[84:87], v[162:165], v[198:201], v[84:87]
	v_mfma_f32_16x16x32_bf16 v[80:83], v[174:177], v[198:201], v[80:83]
	v_mfma_f32_16x16x32_bf16 v[68:71], v[162:165], v[206:209], v[68:71]
	v_mfma_f32_16x16x32_bf16 v[64:67], v[174:177], v[206:209], v[64:67]
	v_mfma_f32_16x16x32_bf16 v[116:119], v[170:173], v[186:189], v[116:119]
	v_mfma_f32_16x16x32_bf16 v[112:115], v[178:181], v[186:189], v[112:115]
	v_mfma_f32_16x16x32_bf16 v[100:103], v[170:173], v[194:197], v[100:103]
	v_mfma_f32_16x16x32_bf16 v[96:99], v[178:181], v[194:197], v[96:99]
	v_mfma_f32_16x16x32_bf16 v[84:87], v[170:173], v[202:205], v[84:87]
	v_mfma_f32_16x16x32_bf16 v[80:83], v[178:181], v[202:205], v[80:83]
	v_mfma_f32_16x16x32_bf16 v[68:71], v[170:173], v[210:213], v[68:71]
	v_mfma_f32_16x16x32_bf16 v[64:67], v[178:181], v[210:213], v[64:67]
	s_setprio 0
	s_barrier
; #define PG8_STAGE(bufoff, gbase, voff) do { _Pragma("unroll") for (int _i = 0; _i < 2; ++_i) \
;         __builtin_amdgcn_global_load_lds((const unsigned*)((const char*)(gbase) + (voff)[_i]), (LAS unsigned*)(lds + (bufoff) + ldsw + _i * 8192), 16, 0, 0); } while (0)
; #define PG8_LDA(dst, b, h) do { _Pragma("unroll") for (int m = 0; m < 4; ++m) _Pragma("unroll") for (int k = 0; k < 2; ++k) dst[m][k] = *(const LAS bf16x8*)(lds + PG8_SA(b, h) + aoff + m * 2048 + k * 1024); } while (0)
; #define PG8_MMA(ai, bj, At, Bt) do { __builtin_amdgcn_s_setprio(1); _Pragma("unroll") for (int m = 0; m < 4; ++m) _Pragma("unroll") for (int n = 0; n < 2; ++n) _Pragma("unroll") for (int k = 0; k < 2; ++k) \
;         acc[ai][bj][m][n] = __builtin_amdgcn_mfma_f32_16x16x32_bf16(Bt[n][k], At[m][k], acc[ai][bj][m][n], 0, 0, 0); __builtin_amdgcn_s_setprio(0); } while (0)
; #define PG8_WAIT_V(n) asm volatile("s_waitcnt vmcnt(" #n ")" ::: "memory")
; #define PG8_WAIT_L(n) asm volatile("s_waitcnt lgkmcnt(" #n ")" ::: "memory")
; #define PG8_BAR __builtin_amdgcn_s_barrier()
; #define PG8_SCHED __builtin_amdgcn_sched_barrier(0)
; template <class Epi, class Sched>
; __device__ __forceinline__ void gemm_phase(LAS unsigned char* lds, const int K, const Sched& S, const Epi& E) {
;     ...
;         for (int t = 0; t < nt; t += 2) {
;     ...
;             PG8_LDA(At, 1, 1); PG8_STAGE(PG8_SB(1, 0), b3, voffB); PG8_STAGE(PG8_SB(1, 1), b3 + hstep, voffB); PG8_STAGE(PG8_SA(1, 0), a3, voffA);
;             PG8_WAIT_V(8); PG8_WAIT_L(0); PG8_BAR; PG8_MMA(1, 0, At, B0); PG8_MMA(1, 1, At, B1); PG8_BAR; PG8_SCHED;
;         }
	s_add_i32 s19, s19, s36
	v_lshl_add_u64 v[166:167], v[166:167], 0, s[10:11]
	s_mov_b32 m0, s19
	ds_read_b128 v[182:185], v149 offset:49152
	ds_read_b128 v[186:189], v149 offset:50176
	ds_read_b128 v[190:193], v149 offset:51200
	ds_read_b128 v[194:197], v149 offset:52224
	ds_read_b128 v[198:201], v149 offset:53248
	ds_read_b128 v[202:205], v149 offset:54272
	ds_read_b128 v[206:209], v149 offset:55296
	ds_read_b128 v[210:213], v149 offset:56320
	global_load_lds_dwordx4 v[166:167], off
	s_add_i32 m0, s19, 0x2000
	s_add_u32 s38, s38, 0x80080
	v_lshl_add_u64 v[166:167], v[214:215], 0, s[10:11]
	s_addc_u32 s39, s39, 0
	s_add_i32 s19, s70, s36
	global_load_lds_dwordx4 v[166:167], off
	v_lshl_add_u64 v[166:167], s[38:39], 0, v[130:131]
	s_mov_b32 m0, s19
	s_nop 0
	global_load_lds_dwordx4 v[166:167], off
	v_lshl_add_u64 v[166:167], s[38:39], 0, v[134:135]
	s_add_i32 m0, s19, 0x2000
	s_nop 0
	global_load_lds_dwordx4 v[166:167], off
	v_lshl_add_u64 v[166:167], v[216:217], 0, s[10:11]
	s_mov_b32 m0, s46
	s_nop 0
	global_load_lds_dwordx4 v[166:167], off
	v_lshl_add_u64 v[166:167], v[218:219], 0, s[10:11]
	s_mov_b32 m0, s47
	s_nop 0
	global_load_lds_dwordx4 v[166:167], off
	s_waitcnt vmcnt(8)
	s_waitcnt lgkmcnt(0)
	s_barrier
	s_setprio 1
	s_waitcnt lgkmcnt(0)
	v_mfma_f32_16x16x32_bf16 v[60:63], v[140:143], v[182:185], v[60:63]
	v_mfma_f32_16x16x32_bf16 v[56:59], v[154:157], v[182:185], v[56:59]
	v_mfma_f32_16x16x32_bf16 v[44:47], v[140:143], v[190:193], v[44:47]
	v_mfma_f32_16x16x32_bf16 v[40:43], v[154:157], v[190:193], v[40:43]
	v_mfma_f32_16x16x32_bf16 v[28:31], v[140:143], v[198:201], v[28:31]
	v_mfma_f32_16x16x32_bf16 v[24:27], v[154:157], v[198:201], v[24:27]
	v_mfma_f32_16x16x32_bf16 v[12:15], v[140:143], v[206:209], v[12:15]
	v_mfma_f32_16x16x32_bf16 v[8:11], v[154:157], v[206:209], v[8:11]
	v_mfma_f32_16x16x32_bf16 v[60:63], v[150:153], v[186:189], v[60:63]
	v_mfma_f32_16x16x32_bf16 v[56:59], v[158:161], v[186:189], v[56:59]
	v_mfma_f32_16x16x32_bf16 v[44:47], v[150:153], v[194:197], v[44:47]
	v_mfma_f32_16x16x32_bf16 v[40:43], v[158:161], v[194:197], v[40:43]
	v_mfma_f32_16x16x32_bf16 v[28:31], v[150:153], v[202:205], v[28:31]
	v_mfma_f32_16x16x32_bf16 v[24:27], v[158:161], v[202:205], v[24:27]
	v_mfma_f32_16x16x32_bf16 v[12:15], v[150:153], v[210:213], v[12:15]
	v_mfma_f32_16x16x32_bf16 v[8:11], v[158:161], v[210:213], v[8:11]
	v_mfma_f32_16x16x32_bf16 v[52:55], v[162:165], v[182:185], v[52:55]
	v_mfma_f32_16x16x32_bf16 v[48:51], v[174:177], v[182:185], v[48:51]
	v_mfma_f32_16x16x32_bf16 v[36:39], v[162:165], v[190:193], v[36:39]
	v_mfma_f32_16x16x32_bf16 v[32:35], v[174:177], v[190:193], v[32:35]
	v_mfma_f32_16x16x32_bf16 v[20:23], v[162:165], v[198:201], v[20:23]
	v_mfma_f32_16x16x32_bf16 v[16:19], v[174:177], v[198:201], v[16:19]
	v_mfma_f32_16x16x32_bf16 v[4:7], v[162:165], v[206:209], v[4:7]
	v_mfma_f32_16x16x32_bf16 v[0:3], v[174:177], v[206:209], v[0:3]
	v_mfma_f32_16x16x32_bf16 v[52:55], v[170:173], v[186:189], v[52:55]
	v_mfma_f32_16x16x32_bf16 v[48:51], v[178:181], v[186:189], v[48:51]
	v_mfma_f32_16x16x32_bf16 v[36:39], v[170:173], v[194:197], v[36:39]
	v_mfma_f32_16x16x32_bf16 v[32:35], v[178:181], v[194:197], v[32:35]
	v_mfma_f32_16x16x32_bf16 v[20:23], v[170:173], v[202:205], v[20:23]
	v_mfma_f32_16x16x32_bf16 v[16:19], v[178:181], v[202:205], v[16:19]
	v_mfma_f32_16x16x32_bf16 v[4:7], v[170:173], v[210:213], v[4:7]
	v_mfma_f32_16x16x32_bf16 v[0:3], v[178:181], v[210:213], v[0:3]
	s_setprio 0
	s_barrier
	s_add_i32 s17, s17, 2
	s_add_u32 s34, s34, 0x100
	s_addc_u32 s35, s35, 0
	s_add_u32 s8, s8, 0x100
	s_addc_u32 s9, s9, 0
	s_cmp_gt_u32 s17, 29
	s_cbranch_scc0 .LBB0_485
	s_and_b64 vcc, exec, s[14:15]
	s_cbranch_vccz .LBB0_488
	s_barrier

; #define PG8_STAGE(bufoff, gbase, voff) do { _Pragma("unroll") for (int _i = 0; _i < 2; ++_i) \
;         __builtin_amdgcn_global_load_lds((const unsigned*)((const char*)(gbase) + (voff)[_i]), (LAS unsigned*)(lds + (bufoff) + ldsw + _i * 8192), 16, 0, 0); } while (0)
; #define PG8_LDA(dst, b, h) do { _Pragma("unroll") for (int m = 0; m < 4; ++m) _Pragma("unroll") for (int k = 0; k < 2; ++k) dst[m][k] = *(const LAS bf16x8*)(lds + PG8_SA(b, h) + aoff + m * 2048 + k * 1024); } while (0)
; #define PG8_LDB(dst, b, h) do { _Pragma("unroll") for (int n = 0; n < 2; ++n) _Pragma("unroll") for (int k = 0; k < 2; ++k) dst[n][k] = *(const LAS bf16x8*)(lds + PG8_SB(b, h) + boff + n * 2048 + k * 1024); } while (0)
; #define PG8_MMA(ai, bj, At, Bt) do { __builtin_amdgcn_s_setprio(1); _Pragma("unroll") for (int m = 0; m < 4; ++m) _Pragma("unroll") for (int n = 0; n < 2; ++n) _Pragma("unroll") for (int k = 0; k < 2; ++k) \
;         acc[ai][bj][m][n] = __builtin_amdgcn_mfma_f32_16x16x32_bf16(Bt[n][k], At[m][k], acc[ai][bj][m][n], 0, 0, 0); __builtin_amdgcn_s_setprio(0); } while (0)
; #define PG8_WAIT_V(n) asm volatile("s_waitcnt vmcnt(" #n ")" ::: "memory")
; #define PG8_WAIT_L(n) asm volatile("s_waitcnt lgkmcnt(" #n ")" ::: "memory")
; #define PG8_BAR __builtin_amdgcn_s_barrier()
; #define PG8_SCHED __builtin_amdgcn_sched_barrier(0)
; template <class Epi, class Sched>
; __device__ __forceinline__ void gemm_phase(LAS unsigned char* lds, const int K, const Sched& S, const Epi& E) {
;     ...
;             PG8_LDB(B0, 0, 0); PG8_LDB(B1, 0, 1); PG8_SCHED; PG8_LDA(At, 0, 0); PG8_STAGE(PG8_SA(1, 1), a1 + hstep, voffA);
;             PG8_WAIT_V(8); PG8_WAIT_L(0); PG8_BAR; PG8_MMA(0, 0, At, B0); PG8_MMA(0, 1, At, B1); PG8_BAR; PG8_SCHED;
;             PG8_LDA(At, 0, 1); PG8_STAGE(PG8_SB(0, 0), b2, voffB); PG8_STAGE(PG8_SB(0, 1), b2 + hstep, voffB); PG8_STAGE(PG8_SA(0, 0), a2, voffA);
;             PG8_WAIT_V(8); PG8_WAIT_L(0); PG8_BAR; PG8_MMA(1, 0, At, B0); PG8_MMA(1, 1, At, B1); PG8_BAR; PG8_SCHED;
.LBB0_565:
	ds_read_b128 v[140:143], v147
	ds_read_b128 v[152:155], v147 offset:1024
	ds_read_b128 v[156:159], v147 offset:2048
	ds_read_b128 v[160:163], v147 offset:3072
	ds_read_b128 v[164:167], v148
	ds_read_b128 v[170:173], v148 offset:1024
	ds_read_b128 v[174:177], v148 offset:2048
	ds_read_b128 v[178:181], v148 offset:3072
	s_add_u32 s24, s22, 0xffea0080
	s_addc_u32 s25, s23, -1
	s_cmpk_eq_i32 s71, 0x54
	s_cselect_b32 s31, s17, s25
	s_cselect_b32 s30, s16, s24
	s_cselect_b32 s25, s19, s9
	s_cselect_b32 s24, s18, s8
	s_mov_b32 m0, s46
	v_lshl_add_u64 v[214:215], s[22:23], 0, v[136:137]
	ds_read_b128 v[182:185], v149
	ds_read_b128 v[186:189], v149 offset:1024
	ds_read_b128 v[190:193], v149 offset:2048
	ds_read_b128 v[194:197], v149 offset:3072
	ds_read_b128 v[198:201], v149 offset:4096
	ds_read_b128 v[202:205], v149 offset:5120
	ds_read_b128 v[206:209], v149 offset:6144
	ds_read_b128 v[210:213], v149 offset:7168
	global_load_lds_dwordx4 v[214:215], off
	v_lshl_add_u64 v[214:215], s[22:23], 0, v[138:139]
	s_mov_b32 m0, s47
	s_nop 0
	global_load_lds_dwordx4 v[214:215], off
	s_waitcnt vmcnt(8)
	s_waitcnt lgkmcnt(0)
	s_barrier
	s_setprio 1
	s_waitcnt lgkmcnt(0)
	v_mfma_f32_16x16x32_bf16 v[124:127], v[140:143], v[182:185], v[124:127]
	v_mfma_f32_16x16x32_bf16 v[120:123], v[156:159], v[182:185], v[120:123]
	v_mfma_f32_16x16x32_bf16 v[108:111], v[140:143], v[190:193], v[108:111]
	v_mfma_f32_16x16x32_bf16 v[104:107], v[156:159], v[190:193], v[104:107]
	v_mfma_f32_16x16x32_bf16 v[92:95], v[140:143], v[198:201], v[92:95]
	v_mfma_f32_16x16x32_bf16 v[88:91], v[156:159], v[198:201], v[88:91]
	v_mfma_f32_16x16x32_bf16 v[76:79], v[140:143], v[206:209], v[76:79]
	v_mfma_f32_16x16x32_bf16 v[72:75], v[156:159], v[206:209], v[72:75]
	v_mfma_f32_16x16x32_bf16 v[124:127], v[152:155], v[186:189], v[124:127]
	v_mfma_f32_16x16x32_bf16 v[120:123], v[160:163], v[186:189], v[120:123]
	v_mfma_f32_16x16x32_bf16 v[108:111], v[152:155], v[194:197], v[108:111]
	v_mfma_f32_16x16x32_bf16 v[104:107], v[160:163], v[194:197], v[104:107]
	v_mfma_f32_16x16x32_bf16 v[92:95], v[152:155], v[202:205], v[92:95]
	v_mfma_f32_16x16x32_bf16 v[88:91], v[160:163], v[202:205], v[88:91]
	v_mfma_f32_16x16x32_bf16 v[76:79], v[152:155], v[210:213], v[76:79]
	v_mfma_f32_16x16x32_bf16 v[72:75], v[160:163], v[210:213], v[72:75]
	v_mfma_f32_16x16x32_bf16 v[116:119], v[164:167], v[182:185], v[116:119]
	v_mfma_f32_16x16x32_bf16 v[112:115], v[174:177], v[182:185], v[112:115]
	v_mfma_f32_16x16x32_bf16 v[100:103], v[164:167], v[190:193], v[100:103]
	v_mfma_f32_16x16x32_bf16 v[96:99], v[174:177], v[190:193], v[96:99]
	v_mfma_f32_16x16x32_bf16 v[84:87], v[164:167], v[198:201], v[84:87]
	v_mfma_f32_16x16x32_bf16 v[80:83], v[174:177], v[198:201], v[80:83]
	v_mfma_f32_16x16x32_bf16 v[68:71], v[164:167], v[206:209], v[68:71]
	v_mfma_f32_16x16x32_bf16 v[64:67], v[174:177], v[206:209], v[64:67]
	v_mfma_f32_16x16x32_bf16 v[116:119], v[170:173], v[186:189], v[116:119]
	v_mfma_f32_16x16x32_bf16 v[112:115], v[178:181], v[186:189], v[112:115]
	v_mfma_f32_16x16x32_bf16 v[100:103], v[170:173], v[194:197], v[100:103]
	v_mfma_f32_16x16x32_bf16 v[96:99], v[178:181], v[194:197], v[96:99]
	v_mfma_f32_16x16x32_bf16 v[84:87], v[170:173], v[202:205], v[84:87]
	v_mfma_f32_16x16x32_bf16 v[80:83], v[178:181], v[202:205], v[80:83]
	v_mfma_f32_16x16x32_bf16 v[68:71], v[170:173], v[210:213], v[68:71]
	v_mfma_f32_16x16x32_bf16 v[64:67], v[178:181], v[210:213], v[64:67]
	s_setprio 0
	s_barrier
	s_mov_b32 m0, s48
	v_lshl_add_u64 v[214:215], s[24:25], 0, v[130:131]
	s_add_u32 s72, s24, 0x160000
	ds_read_b128 v[182:185], v149 offset:16384
	ds_read_b128 v[186:189], v149 offset:17408
	ds_read_b128 v[190:193], v149 offset:18432
	ds_read_b128 v[194:197], v149 offset:19456
	ds_read_b128 v[198:201], v149 offset:20480
	ds_read_b128 v[202:205], v149 offset:21504
	ds_read_b128 v[206:209], v149 offset:22528
	ds_read_b128 v[210:213], v149 offset:23552
	global_load_lds_dwordx4 v[214:215], off
	v_lshl_add_u64 v[216:217], s[24:25], 0, v[134:135]
	s_mov_b32 m0, s49
	s_addc_u32 s73, s25, 0
	global_load_lds_dwordx4 v[216:217], off
	v_lshl_add_u64 v[218:219], s[72:73], 0, v[130:131]
	s_mov_b32 m0, s50
	v_lshl_add_u64 v[220:221], s[30:31], 0, v[132:133]
	global_load_lds_dwordx4 v[218:219], off
	v_lshl_add_u64 v[218:219], s[72:73], 0, v[134:135]
	s_add_i32 m0, s50, 0x2000
	s_nop 0
	global_load_lds_dwordx4 v[218:219], off
	v_lshl_add_u64 v[218:219], s[30:31], 0, v[128:129]
	s_mov_b32 m0, s37
	s_nop 0
	global_load_lds_dwordx4 v[218:219], off
	s_mov_b32 m0, s38
	s_nop 0
	global_load_lds_dwordx4 v[220:221], off
	s_waitcnt vmcnt(8)
	s_waitcnt lgkmcnt(0)
	s_barrier
; #define PG8_STAGE(bufoff, gbase, voff) do { _Pragma("unroll") for (int _i = 0; _i < 2; ++_i) \
;         __builtin_amdgcn_global_load_lds((const unsigned*)((const char*)(gbase) + (voff)[_i]), (LAS unsigned*)(lds + (bufoff) + ldsw + _i * 8192), 16, 0, 0); } while (0)
; #define PG8_LDA(dst, b, h) do { _Pragma("unroll") for (int m = 0; m < 4; ++m) _Pragma("unroll") for (int k = 0; k < 2; ++k) dst[m][k] = *(const LAS bf16x8*)(lds + PG8_SA(b, h) + aoff + m * 2048 + k * 1024); } while (0)
; #define PG8_LDB(dst, b, h) do { _Pragma("unroll") for (int n = 0; n < 2; ++n) _Pragma("unroll") for (int k = 0; k < 2; ++k) dst[n][k] = *(const LAS bf16x8*)(lds + PG8_SB(b, h) + boff + n * 2048 + k * 1024); } while (0)
; #define PG8_MMA(ai, bj, At, Bt) do { __builtin_amdgcn_s_setprio(1); _Pragma("unroll") for (int m = 0; m < 4; ++m) _Pragma("unroll") for (int n = 0; n < 2; ++n) _Pragma("unroll") for (int k = 0; k < 2; ++k) \
;         acc[ai][bj][m][n] = __builtin_amdgcn_mfma_f32_16x16x32_bf16(Bt[n][k], At[m][k], acc[ai][bj][m][n], 0, 0, 0); __builtin_amdgcn_s_setprio(0); } while (0)
; #define PG8_WAIT_V(n) asm volatile("s_waitcnt vmcnt(" #n ")" ::: "memory")
; #define PG8_WAIT_L(n) asm volatile("s_waitcnt lgkmcnt(" #n ")" ::: "memory")
; #define PG8_BAR __builtin_amdgcn_s_barrier()
; #define PG8_SCHED __builtin_amdgcn_sched_barrier(0)
; template <class Epi, class Sched>
; __device__ __forceinline__ void gemm_phase(LAS unsigned char* lds, const int K, const Sched& S, const Epi& E) {
;     ...
;             PG8_WAIT_V(8); PG8_WAIT_L(0); PG8_BAR; PG8_MMA(1, 0, At, B0); PG8_MMA(1, 1, At, B1); PG8_BAR; PG8_SCHED;
;             PG8_LDB(B0, 1, 0); PG8_LDB(B1, 1, 1); PG8_SCHED; PG8_LDA(At, 1, 0); PG8_STAGE(PG8_SA(0, 1), a2 + hstep, voffA);
;             PG8_WAIT_V(8); PG8_WAIT_L(0); PG8_BAR; PG8_MMA(0, 0, At, B0); PG8_MMA(0, 1, At, B1); PG8_BAR; PG8_SCHED;
	s_setprio 1
	s_waitcnt lgkmcnt(0)
	v_mfma_f32_16x16x32_bf16 v[60:63], v[140:143], v[182:185], v[60:63]
	v_mfma_f32_16x16x32_bf16 v[56:59], v[156:159], v[182:185], v[56:59]
	v_mfma_f32_16x16x32_bf16 v[44:47], v[140:143], v[190:193], v[44:47]
	v_mfma_f32_16x16x32_bf16 v[40:43], v[156:159], v[190:193], v[40:43]
	v_mfma_f32_16x16x32_bf16 v[28:31], v[140:143], v[198:201], v[28:31]
	v_mfma_f32_16x16x32_bf16 v[24:27], v[156:159], v[198:201], v[24:27]
	v_mfma_f32_16x16x32_bf16 v[12:15], v[140:143], v[206:209], v[12:15]
	v_mfma_f32_16x16x32_bf16 v[8:11], v[156:159], v[206:209], v[8:11]
	v_mfma_f32_16x16x32_bf16 v[60:63], v[152:155], v[186:189], v[60:63]
	v_mfma_f32_16x16x32_bf16 v[56:59], v[160:163], v[186:189], v[56:59]
	v_mfma_f32_16x16x32_bf16 v[44:47], v[152:155], v[194:197], v[44:47]
	v_mfma_f32_16x16x32_bf16 v[40:43], v[160:163], v[194:197], v[40:43]
	v_mfma_f32_16x16x32_bf16 v[28:31], v[152:155], v[202:205], v[28:31]
	v_mfma_f32_16x16x32_bf16 v[24:27], v[160:163], v[202:205], v[24:27]
	v_mfma_f32_16x16x32_bf16 v[12:15], v[152:155], v[210:213], v[12:15]
	v_mfma_f32_16x16x32_bf16 v[8:11], v[160:163], v[210:213], v[8:11]
	v_mfma_f32_16x16x32_bf16 v[52:55], v[164:167], v[182:185], v[52:55]
	v_mfma_f32_16x16x32_bf16 v[48:51], v[174:177], v[182:185], v[48:51]
	v_mfma_f32_16x16x32_bf16 v[36:39], v[164:167], v[190:193], v[36:39]
	v_mfma_f32_16x16x32_bf16 v[32:35], v[174:177], v[190:193], v[32:35]
	v_mfma_f32_16x16x32_bf16 v[20:23], v[164:167], v[198:201], v[20:23]
	v_mfma_f32_16x16x32_bf16 v[16:19], v[174:177], v[198:201], v[16:19]
	v_mfma_f32_16x16x32_bf16 v[4:7], v[164:167], v[206:209], v[4:7]
	v_mfma_f32_16x16x32_bf16 v[0:3], v[174:177], v[206:209], v[0:3]
	v_mfma_f32_16x16x32_bf16 v[52:55], v[170:173], v[186:189], v[52:55]
	v_mfma_f32_16x16x32_bf16 v[48:51], v[178:181], v[186:189], v[48:51]
	v_mfma_f32_16x16x32_bf16 v[36:39], v[170:173], v[194:197], v[36:39]
	v_mfma_f32_16x16x32_bf16 v[32:35], v[178:181], v[194:197], v[32:35]
	v_mfma_f32_16x16x32_bf16 v[20:23], v[170:173], v[202:205], v[20:23]
	v_mfma_f32_16x16x32_bf16 v[16:19], v[178:181], v[202:205], v[16:19]
	v_mfma_f32_16x16x32_bf16 v[4:7], v[170:173], v[210:213], v[4:7]
	v_mfma_f32_16x16x32_bf16 v[0:3], v[178:181], v[210:213], v[0:3]
	s_setprio 0
	s_barrier
	s_add_i32 s72, 0, 0x18000
	v_add_u32_e32 v151, s72, v146
	s_add_i32 s73, 0, 0x1c000
	ds_read_b128 v[140:143], v151
	ds_read_b128 v[152:155], v151 offset:1024
	ds_read_b128 v[156:159], v151 offset:2048
	ds_read_b128 v[160:163], v151 offset:3072
	v_add_u32_e32 v151, s73, v146
	ds_read_b128 v[164:167], v151
	ds_read_b128 v[170:173], v151 offset:1024
	ds_read_b128 v[174:177], v151 offset:2048
	ds_read_b128 v[178:181], v151 offset:3072
	s_add_u32 s30, s30, 0x160000
	s_addc_u32 s31, s31, 0
	s_mov_b32 m0, s39
	v_lshl_add_u64 v[224:225], s[30:31], 0, v[128:129]
	ds_read_b128 v[182:185], v149 offset:32768
	ds_read_b128 v[186:189], v149 offset:33792
	ds_read_b128 v[190:193], v149 offset:34816
	ds_read_b128 v[194:197], v149 offset:35840
	ds_read_b128 v[198:201], v149 offset:36864
	ds_read_b128 v[202:205], v149 offset:37888
	ds_read_b128 v[206:209], v149 offset:38912
	ds_read_b128 v[210:213], v149 offset:39936
	global_load_lds_dwordx4 v[224:225], off
	v_lshl_add_u64 v[224:225], s[30:31], 0, v[132:133]
	s_mov_b32 m0, s40
	s_nop 0
	global_load_lds_dwordx4 v[224:225], off
	s_waitcnt vmcnt(8)
	s_waitcnt lgkmcnt(0)
	s_barrier
	s_setprio 1
	s_waitcnt lgkmcnt(0)
	v_mfma_f32_16x16x32_bf16 v[124:127], v[140:143], v[182:185], v[124:127]
	v_mfma_f32_16x16x32_bf16 v[120:123], v[156:159], v[182:185], v[120:123]
	v_mfma_f32_16x16x32_bf16 v[108:111], v[140:143], v[190:193], v[108:111]
	v_mfma_f32_16x16x32_bf16 v[104:107], v[156:159], v[190:193], v[104:107]
	v_mfma_f32_16x16x32_bf16 v[92:95], v[140:143], v[198:201], v[92:95]
	v_mfma_f32_16x16x32_bf16 v[88:91], v[156:159], v[198:201], v[88:91]
	v_mfma_f32_16x16x32_bf16 v[76:79], v[140:143], v[206:209], v[76:79]
	v_mfma_f32_16x16x32_bf16 v[72:75], v[156:159], v[206:209], v[72:75]
	v_mfma_f32_16x16x32_bf16 v[124:127], v[152:155], v[186:189], v[124:127]
	v_mfma_f32_16x16x32_bf16 v[120:123], v[160:163], v[186:189], v[120:123]
	v_mfma_f32_16x16x32_bf16 v[108:111], v[152:155], v[194:197], v[108:111]
	v_mfma_f32_16x16x32_bf16 v[104:107], v[160:163], v[194:197], v[104:107]
	v_mfma_f32_16x16x32_bf16 v[92:95], v[152:155], v[202:205], v[92:95]
	v_mfma_f32_16x16x32_bf16 v[88:91], v[160:163], v[202:205], v[88:91]
	v_mfma_f32_16x16x32_bf16 v[76:79], v[152:155], v[210:213], v[76:79]
	v_mfma_f32_16x16x32_bf16 v[72:75], v[160:163], v[210:213], v[72:75]
	v_mfma_f32_16x16x32_bf16 v[116:119], v[164:167], v[182:185], v[116:119]
	v_mfma_f32_16x16x32_bf16 v[112:115], v[174:177], v[182:185], v[112:115]
	v_mfma_f32_16x16x32_bf16 v[100:103], v[164:167], v[190:193], v[100:103]
	v_mfma_f32_16x16x32_bf16 v[96:99], v[174:177], v[190:193], v[96:99]
	v_mfma_f32_16x16x32_bf16 v[84:87], v[164:167], v[198:201], v[84:87]
	v_mfma_f32_16x16x32_bf16 v[80:83], v[174:177], v[198:201], v[80:83]
	v_mfma_f32_16x16x32_bf16 v[68:71], v[164:167], v[206:209], v[68:71]
	v_mfma_f32_16x16x32_bf16 v[64:67], v[174:177], v[206:209], v[64:67]
	v_mfma_f32_16x16x32_bf16 v[116:119], v[170:173], v[186:189], v[116:119]
	v_mfma_f32_16x16x32_bf16 v[112:115], v[178:181], v[186:189], v[112:115]
	v_mfma_f32_16x16x32_bf16 v[100:103], v[170:173], v[194:197], v[100:103]
	v_mfma_f32_16x16x32_bf16 v[96:99], v[178:181], v[194:197], v[96:99]
	v_mfma_f32_16x16x32_bf16 v[84:87], v[170:173], v[202:205], v[84:87]
	v_mfma_f32_16x16x32_bf16 v[80:83], v[178:181], v[202:205], v[80:83]
	v_mfma_f32_16x16x32_bf16 v[68:71], v[170:173], v[210:213], v[68:71]
	v_mfma_f32_16x16x32_bf16 v[64:67], v[178:181], v[210:213], v[64:67]
	s_setprio 0
	s_barrier
; #define PG8_STAGE(bufoff, gbase, voff) do { _Pragma("unroll") for (int _i = 0; _i < 2; ++_i) \
;         __builtin_amdgcn_global_load_lds((const unsigned*)((const char*)(gbase) + (voff)[_i]), (LAS unsigned*)(lds + (bufoff) + ldsw + _i * 8192), 16, 0, 0); } while (0)
; #define PG8_LDA(dst, b, h) do { _Pragma("unroll") for (int m = 0; m < 4; ++m) _Pragma("unroll") for (int k = 0; k < 2; ++k) dst[m][k] = *(const LAS bf16x8*)(lds + PG8_SA(b, h) + aoff + m * 2048 + k * 1024); } while (0)
; #define PG8_MMA(ai, bj, At, Bt) do { __builtin_amdgcn_s_setprio(1); _Pragma("unroll") for (int m = 0; m < 4; ++m) _Pragma("unroll") for (int n = 0; n < 2; ++n) _Pragma("unroll") for (int k = 0; k < 2; ++k) \
;         acc[ai][bj][m][n] = __builtin_amdgcn_mfma_f32_16x16x32_bf16(Bt[n][k], At[m][k], acc[ai][bj][m][n], 0, 0, 0); __builtin_amdgcn_s_setprio(0); } while (0)
; #define PG8_WAIT_V(n) asm volatile("s_waitcnt vmcnt(" #n ")" ::: "memory")
; #define PG8_WAIT_L(n) asm volatile("s_waitcnt lgkmcnt(" #n ")" ::: "memory")
; #define PG8_BAR __builtin_amdgcn_s_barrier()
; #define PG8_SCHED __builtin_amdgcn_sched_barrier(0)
; template <class Epi, class Sched>
; __device__ __forceinline__ void gemm_phase(LAS unsigned char* lds, const int K, const Sched& S, const Epi& E) {
;     ...
;         for (int t = 0; t < nt; t += 2) {
;     ...
;             PG8_LDA(At, 1, 1); PG8_STAGE(PG8_SB(1, 0), b3, voffB); PG8_STAGE(PG8_SB(1, 1), b3 + hstep, voffB); PG8_STAGE(PG8_SA(1, 0), a3, voffA);
;             PG8_WAIT_V(8); PG8_WAIT_L(0); PG8_BAR; PG8_MMA(1, 0, At, B0); PG8_MMA(1, 1, At, B1); PG8_BAR; PG8_SCHED;
;         }
	s_add_i32 s30, s72, s36
	v_lshl_add_u64 v[214:215], v[214:215], 0, s[10:11]
	s_mov_b32 m0, s30
	ds_read_b128 v[182:185], v149 offset:49152
	ds_read_b128 v[186:189], v149 offset:50176
	ds_read_b128 v[190:193], v149 offset:51200
	ds_read_b128 v[194:197], v149 offset:52224
	ds_read_b128 v[198:201], v149 offset:53248
	ds_read_b128 v[202:205], v149 offset:54272
	ds_read_b128 v[206:209], v149 offset:55296
	ds_read_b128 v[210:213], v149 offset:56320
	global_load_lds_dwordx4 v[214:215], off
	s_add_i32 m0, s30, 0x2000
	s_add_u32 s24, s24, 0x160080
	v_lshl_add_u64 v[214:215], v[216:217], 0, s[10:11]
	s_addc_u32 s25, s25, 0
	s_add_i32 s30, s73, s36
	global_load_lds_dwordx4 v[214:215], off
	v_lshl_add_u64 v[214:215], s[24:25], 0, v[130:131]
	s_mov_b32 m0, s30
	s_nop 0
	global_load_lds_dwordx4 v[214:215], off
	v_lshl_add_u64 v[214:215], s[24:25], 0, v[134:135]
	s_add_i32 m0, s30, 0x2000
	s_nop 0
	global_load_lds_dwordx4 v[214:215], off
	v_lshl_add_u64 v[214:215], v[218:219], 0, s[10:11]
	s_mov_b32 m0, s44
	s_nop 0
	global_load_lds_dwordx4 v[214:215], off
	v_lshl_add_u64 v[214:215], v[220:221], 0, s[10:11]
	s_mov_b32 m0, s45
	s_nop 0
	global_load_lds_dwordx4 v[214:215], off
	s_waitcnt vmcnt(8)
	s_waitcnt lgkmcnt(0)
	s_barrier
	s_setprio 1
	s_waitcnt lgkmcnt(0)
	v_mfma_f32_16x16x32_bf16 v[60:63], v[140:143], v[182:185], v[60:63]
	v_mfma_f32_16x16x32_bf16 v[56:59], v[156:159], v[182:185], v[56:59]
	v_mfma_f32_16x16x32_bf16 v[44:47], v[140:143], v[190:193], v[44:47]
	v_mfma_f32_16x16x32_bf16 v[40:43], v[156:159], v[190:193], v[40:43]
	v_mfma_f32_16x16x32_bf16 v[28:31], v[140:143], v[198:201], v[28:31]
	v_mfma_f32_16x16x32_bf16 v[24:27], v[156:159], v[198:201], v[24:27]
	v_mfma_f32_16x16x32_bf16 v[12:15], v[140:143], v[206:209], v[12:15]
	v_mfma_f32_16x16x32_bf16 v[8:11], v[156:159], v[206:209], v[8:11]
	v_mfma_f32_16x16x32_bf16 v[60:63], v[152:155], v[186:189], v[60:63]
	v_mfma_f32_16x16x32_bf16 v[56:59], v[160:163], v[186:189], v[56:59]
	v_mfma_f32_16x16x32_bf16 v[44:47], v[152:155], v[194:197], v[44:47]
	v_mfma_f32_16x16x32_bf16 v[40:43], v[160:163], v[194:197], v[40:43]
	v_mfma_f32_16x16x32_bf16 v[28:31], v[152:155], v[202:205], v[28:31]
	v_mfma_f32_16x16x32_bf16 v[24:27], v[160:163], v[202:205], v[24:27]
	v_mfma_f32_16x16x32_bf16 v[12:15], v[152:155], v[210:213], v[12:15]
	v_mfma_f32_16x16x32_bf16 v[8:11], v[160:163], v[210:213], v[8:11]
	v_mfma_f32_16x16x32_bf16 v[52:55], v[164:167], v[182:185], v[52:55]
	v_mfma_f32_16x16x32_bf16 v[48:51], v[174:177], v[182:185], v[48:51]
	v_mfma_f32_16x16x32_bf16 v[36:39], v[164:167], v[190:193], v[36:39]
	v_mfma_f32_16x16x32_bf16 v[32:35], v[174:177], v[190:193], v[32:35]
	v_mfma_f32_16x16x32_bf16 v[20:23], v[164:167], v[198:201], v[20:23]
	v_mfma_f32_16x16x32_bf16 v[16:19], v[174:177], v[198:201], v[16:19]
	v_mfma_f32_16x16x32_bf16 v[4:7], v[164:167], v[206:209], v[4:7]
	v_mfma_f32_16x16x32_bf16 v[0:3], v[174:177], v[206:209], v[0:3]
	v_mfma_f32_16x16x32_bf16 v[52:55], v[170:173], v[186:189], v[52:55]
	v_mfma_f32_16x16x32_bf16 v[48:51], v[178:181], v[186:189], v[48:51]
	v_mfma_f32_16x16x32_bf16 v[36:39], v[170:173], v[194:197], v[36:39]
	v_mfma_f32_16x16x32_bf16 v[32:35], v[178:181], v[194:197], v[32:35]
	v_mfma_f32_16x16x32_bf16 v[20:23], v[170:173], v[202:205], v[20:23]
	v_mfma_f32_16x16x32_bf16 v[16:19], v[178:181], v[202:205], v[16:19]
	v_mfma_f32_16x16x32_bf16 v[4:7], v[170:173], v[210:213], v[4:7]
	v_mfma_f32_16x16x32_bf16 v[0:3], v[178:181], v[210:213], v[0:3]
	s_setprio 0
	s_barrier
	s_add_i32 s71, s71, 2
	s_add_u32 s22, s22, 0x100
	s_addc_u32 s23, s23, 0
	s_add_u32 s8, s8, 0x100
	s_addc_u32 s9, s9, 0
	s_cmpk_gt_u32 s71, 0x55
	s_cbranch_scc0 .LBB0_565
	s_and_b64 vcc, exec, s[14:15]
	s_cbranch_vccz .LBB0_568
	s_barrier

; #define PG8_STAGE(bufoff, gbase, voff) do { _Pragma("unroll") for (int _i = 0; _i < 2; ++_i) \
;         __builtin_amdgcn_global_load_lds((const unsigned*)((const char*)(gbase) + (voff)[_i]), (LAS unsigned*)(lds + (bufoff) + ldsw + _i * 8192), 16, 0, 0); } while (0)
; #define PG8_LDA(dst, b, h) do { _Pragma("unroll") for (int m = 0; m < 4; ++m) _Pragma("unroll") for (int k = 0; k < 2; ++k) dst[m][k] = *(const LAS bf16x8*)(lds + PG8_SA(b, h) + aoff + m * 2048 + k * 1024); } while (0)
; #define PG8_LDB(dst, b, h) do { _Pragma("unroll") for (int n = 0; n < 2; ++n) _Pragma("unroll") for (int k = 0; k < 2; ++k) dst[n][k] = *(const LAS bf16x8*)(lds + PG8_SB(b, h) + boff + n * 2048 + k * 1024); } while (0)
; #define PG8_MMA(ai, bj, At, Bt) do { __builtin_amdgcn_s_setprio(1); _Pragma("unroll") for (int m = 0; m < 4; ++m) _Pragma("unroll") for (int n = 0; n < 2; ++n) _Pragma("unroll") for (int k = 0; k < 2; ++k) \
;         acc[ai][bj][m][n] = __builtin_amdgcn_mfma_f32_16x16x32_bf16(Bt[n][k], At[m][k], acc[ai][bj][m][n], 0, 0, 0); __builtin_amdgcn_s_setprio(0); } while (0)
; #define PG8_WAIT_V(n) asm volatile("s_waitcnt vmcnt(" #n ")" ::: "memory")
; #define PG8_WAIT_L(n) asm volatile("s_waitcnt lgkmcnt(" #n ")" ::: "memory")
; #define PG8_BAR __builtin_amdgcn_s_barrier()
; #define PG8_SCHED __builtin_amdgcn_sched_barrier(0)
; template <class Epi, class Sched>
; __device__ __forceinline__ void gemm_phase(LAS unsigned char* lds, const int K, const Sched& S, const Epi& E) {
;     ...
;             PG8_LDB(B0, 0, 0); PG8_LDB(B1, 0, 1); PG8_SCHED; PG8_LDA(At, 0, 0); PG8_STAGE(PG8_SA(1, 1), a1 + hstep, voffA);
;             PG8_WAIT_V(8); PG8_WAIT_L(0); PG8_BAR; PG8_MMA(0, 0, At, B0); PG8_MMA(0, 1, At, B1); PG8_BAR; PG8_SCHED;
;             PG8_LDA(At, 0, 1); PG8_STAGE(PG8_SB(0, 0), b2, voffB); PG8_STAGE(PG8_SB(0, 1), b2 + hstep, voffB); PG8_STAGE(PG8_SA(0, 0), a2, voffA);
;             PG8_WAIT_V(8); PG8_WAIT_L(0); PG8_BAR; PG8_MMA(1, 0, At, B0); PG8_MMA(1, 1, At, B1); PG8_BAR; PG8_SCHED;
.LBB0_661:
	ds_read_b128 v[0:3], v227
	ds_read_b128 v[4:7], v227 offset:1024
	ds_read_b128 v[8:11], v227 offset:2048
	ds_read_b128 v[12:15], v227 offset:3072
	ds_read_b128 v[16:19], v228
	ds_read_b128 v[20:23], v228 offset:1024
	ds_read_b128 v[152:155], v228 offset:2048
	ds_read_b128 v[156:159], v228 offset:3072
	s_add_u32 s36, s6, 0xfff80080
	s_addc_u32 s37, s7, -1
	s_cmp_eq_u32 s9, 28
	s_cselect_b32 s75, s69, s37
	s_cselect_b32 s74, s68, s36
	s_cselect_b32 s73, s71, s8
	s_cselect_b32 s72, s70, s1
	v_lshl_add_u64 v[210:211], s[6:7], 0, v[180:181]
	s_add_i32 m0, s47, 0xc000
	ds_read_b128 v[160:163], v229
	ds_read_b128 v[164:167], v229 offset:1024
	ds_read_b128 v[186:189], v229 offset:2048
	ds_read_b128 v[190:193], v229 offset:3072
	ds_read_b128 v[194:197], v229 offset:4096
	ds_read_b128 v[198:201], v229 offset:5120
	ds_read_b128 v[202:205], v229 offset:6144
	ds_read_b128 v[206:209], v229 offset:7168
	global_load_lds_dwordx4 v[210:211], off
	v_lshl_add_u64 v[210:211], s[6:7], 0, v[182:183]
	s_add_i32 m0, s47, 0xe000
	s_nop 0
	global_load_lds_dwordx4 v[210:211], off
	s_waitcnt vmcnt(8)
	s_waitcnt lgkmcnt(0)
	s_barrier
	s_setprio 1
	s_waitcnt lgkmcnt(0)
	v_mfma_f32_16x16x32_bf16 v[148:151], v[0:3], v[160:163], v[148:151]
	v_mfma_f32_16x16x32_bf16 v[144:147], v[8:11], v[160:163], v[144:147]
	v_mfma_f32_16x16x32_bf16 v[132:135], v[0:3], v[186:189], v[132:135]
	v_mfma_f32_16x16x32_bf16 v[128:131], v[8:11], v[186:189], v[128:131]
	v_mfma_f32_16x16x32_bf16 v[116:119], v[0:3], v[194:197], v[116:119]
	v_mfma_f32_16x16x32_bf16 v[112:115], v[8:11], v[194:197], v[112:115]
	v_mfma_f32_16x16x32_bf16 v[100:103], v[0:3], v[202:205], v[100:103]
	v_mfma_f32_16x16x32_bf16 v[96:99], v[8:11], v[202:205], v[96:99]
	v_mfma_f32_16x16x32_bf16 v[148:151], v[4:7], v[164:167], v[148:151]
	v_mfma_f32_16x16x32_bf16 v[144:147], v[12:15], v[164:167], v[144:147]
	v_mfma_f32_16x16x32_bf16 v[132:135], v[4:7], v[190:193], v[132:135]
	v_mfma_f32_16x16x32_bf16 v[128:131], v[12:15], v[190:193], v[128:131]
	v_mfma_f32_16x16x32_bf16 v[116:119], v[4:7], v[198:201], v[116:119]
	v_mfma_f32_16x16x32_bf16 v[112:115], v[12:15], v[198:201], v[112:115]
	v_mfma_f32_16x16x32_bf16 v[100:103], v[4:7], v[206:209], v[100:103]
	v_mfma_f32_16x16x32_bf16 v[96:99], v[12:15], v[206:209], v[96:99]
	v_mfma_f32_16x16x32_bf16 v[140:143], v[16:19], v[160:163], v[140:143]
	v_mfma_f32_16x16x32_bf16 v[136:139], v[152:155], v[160:163], v[136:139]
	v_mfma_f32_16x16x32_bf16 v[124:127], v[16:19], v[186:189], v[124:127]
	v_mfma_f32_16x16x32_bf16 v[120:123], v[152:155], v[186:189], v[120:123]
	v_mfma_f32_16x16x32_bf16 v[108:111], v[16:19], v[194:197], v[108:111]
	v_mfma_f32_16x16x32_bf16 v[104:107], v[152:155], v[194:197], v[104:107]
	v_mfma_f32_16x16x32_bf16 v[92:95], v[16:19], v[202:205], v[92:95]
	v_mfma_f32_16x16x32_bf16 v[88:91], v[152:155], v[202:205], v[88:91]
	v_mfma_f32_16x16x32_bf16 v[140:143], v[20:23], v[164:167], v[140:143]
	v_mfma_f32_16x16x32_bf16 v[136:139], v[156:159], v[164:167], v[136:139]
	v_mfma_f32_16x16x32_bf16 v[124:127], v[20:23], v[190:193], v[124:127]
	v_mfma_f32_16x16x32_bf16 v[120:123], v[156:159], v[190:193], v[120:123]
	v_mfma_f32_16x16x32_bf16 v[108:111], v[20:23], v[198:201], v[108:111]
	v_mfma_f32_16x16x32_bf16 v[104:107], v[156:159], v[198:201], v[104:107]
	v_mfma_f32_16x16x32_bf16 v[92:95], v[20:23], v[206:209], v[92:95]
	v_mfma_f32_16x16x32_bf16 v[88:91], v[156:159], v[206:209], v[88:91]
	s_setprio 0
	s_barrier
	s_add_i32 s36, s92, s45
	v_lshl_add_u64 v[218:219], s[72:73], 0, v[172:173]
	s_mov_b32 m0, s36
	ds_read_b128 v[160:163], v229 offset:16384
	ds_read_b128 v[164:167], v229 offset:17408
	ds_read_b128 v[186:189], v229 offset:18432
	ds_read_b128 v[190:193], v229 offset:19456
	ds_read_b128 v[194:197], v229 offset:20480
	ds_read_b128 v[198:201], v229 offset:21504
	ds_read_b128 v[202:205], v229 offset:22528
	ds_read_b128 v[206:209], v229 offset:23552
	global_load_lds_dwordx4 v[218:219], off
	s_add_i32 m0, s36, 0x2000
	s_add_u32 s36, s72, 0x80000
	v_lshl_add_u64 v[220:221], s[72:73], 0, v[176:177]
	s_addc_u32 s37, s73, 0
	s_add_i32 s42, s93, s45
	global_load_lds_dwordx4 v[220:221], off
	v_lshl_add_u64 v[210:211], s[36:37], 0, v[172:173]
	s_mov_b32 m0, s42
	v_lshl_add_u64 v[232:233], s[74:75], 0, v[170:171]
	global_load_lds_dwordx4 v[210:211], off
	v_lshl_add_u64 v[210:211], s[36:37], 0, v[176:177]
	s_add_i32 m0, s42, 0x2000
	v_lshl_add_u64 v[234:235], s[74:75], 0, v[174:175]
	global_load_lds_dwordx4 v[210:211], off
	s_mov_b32 m0, s47
	s_nop 0
	global_load_lds_dwordx4 v[232:233], off
	s_mov_b32 m0, s76
	s_nop 0
	global_load_lds_dwordx4 v[234:235], off
	s_waitcnt vmcnt(8)
	s_waitcnt lgkmcnt(0)
	s_barrier
; #define PG8_STAGE(bufoff, gbase, voff) do { _Pragma("unroll") for (int _i = 0; _i < 2; ++_i) \
;         __builtin_amdgcn_global_load_lds((const unsigned*)((const char*)(gbase) + (voff)[_i]), (LAS unsigned*)(lds + (bufoff) + ldsw + _i * 8192), 16, 0, 0); } while (0)
; #define PG8_LDA(dst, b, h) do { _Pragma("unroll") for (int m = 0; m < 4; ++m) _Pragma("unroll") for (int k = 0; k < 2; ++k) dst[m][k] = *(const LAS bf16x8*)(lds + PG8_SA(b, h) + aoff + m * 2048 + k * 1024); } while (0)
; #define PG8_LDB(dst, b, h) do { _Pragma("unroll") for (int n = 0; n < 2; ++n) _Pragma("unroll") for (int k = 0; k < 2; ++k) dst[n][k] = *(const LAS bf16x8*)(lds + PG8_SB(b, h) + boff + n * 2048 + k * 1024); } while (0)
; #define PG8_MMA(ai, bj, At, Bt) do { __builtin_amdgcn_s_setprio(1); _Pragma("unroll") for (int m = 0; m < 4; ++m) _Pragma("unroll") for (int n = 0; n < 2; ++n) _Pragma("unroll") for (int k = 0; k < 2; ++k) \
;         acc[ai][bj][m][n] = __builtin_amdgcn_mfma_f32_16x16x32_bf16(Bt[n][k], At[m][k], acc[ai][bj][m][n], 0, 0, 0); __builtin_amdgcn_s_setprio(0); } while (0)
; #define PG8_WAIT_V(n) asm volatile("s_waitcnt vmcnt(" #n ")" ::: "memory")
; #define PG8_WAIT_L(n) asm volatile("s_waitcnt lgkmcnt(" #n ")" ::: "memory")
; #define PG8_BAR __builtin_amdgcn_s_barrier()
; #define PG8_SCHED __builtin_amdgcn_sched_barrier(0)
; template <class Epi, class Sched>
; __device__ __forceinline__ void gemm_phase(LAS unsigned char* lds, const int K, const Sched& S, const Epi& E) {
;     ...
;             PG8_WAIT_V(8); PG8_WAIT_L(0); PG8_BAR; PG8_MMA(1, 0, At, B0); PG8_MMA(1, 1, At, B1); PG8_BAR; PG8_SCHED;
;             PG8_LDB(B0, 1, 0); PG8_LDB(B1, 1, 1); PG8_SCHED; PG8_LDA(At, 1, 0); PG8_STAGE(PG8_SA(0, 1), a2 + hstep, voffA);
;             PG8_WAIT_V(8); PG8_WAIT_L(0); PG8_BAR; PG8_MMA(0, 0, At, B0); PG8_MMA(0, 1, At, B1); PG8_BAR; PG8_SCHED;
	s_setprio 1
	s_waitcnt lgkmcnt(0)
	v_mfma_f32_16x16x32_bf16 v[84:87], v[0:3], v[160:163], v[84:87]
	v_mfma_f32_16x16x32_bf16 v[80:83], v[8:11], v[160:163], v[80:83]
	v_mfma_f32_16x16x32_bf16 v[68:71], v[0:3], v[186:189], v[68:71]
	v_mfma_f32_16x16x32_bf16 v[64:67], v[8:11], v[186:189], v[64:67]
	v_mfma_f32_16x16x32_bf16 v[52:55], v[0:3], v[194:197], v[52:55]
	v_mfma_f32_16x16x32_bf16 v[48:51], v[8:11], v[194:197], v[48:51]
	v_mfma_f32_16x16x32_bf16 v[0:3], v[0:3], v[202:205], v[36:39]
	v_mfma_f32_16x16x32_bf16 v[84:87], v[4:7], v[164:167], v[84:87]
	v_mfma_f32_16x16x32_bf16 v[80:83], v[12:15], v[164:167], v[80:83]
	v_mfma_f32_16x16x32_bf16 v[68:71], v[4:7], v[190:193], v[68:71]
	v_mfma_f32_16x16x32_bf16 v[64:67], v[12:15], v[190:193], v[64:67]
	v_mfma_f32_16x16x32_bf16 v[52:55], v[4:7], v[198:201], v[52:55]
	v_mfma_f32_16x16x32_bf16 v[48:51], v[12:15], v[198:201], v[48:51]
	v_mfma_f32_16x16x32_bf16 v[0:3], v[4:7], v[206:209], v[0:3]
	v_mfma_f32_16x16x32_bf16 v[4:7], v[8:11], v[202:205], v[32:35]
	v_mfma_f32_16x16x32_bf16 v[4:7], v[12:15], v[206:209], v[4:7]
	v_mfma_f32_16x16x32_bf16 v[32:35], v[16:19], v[186:189], v[60:63]
	v_mfma_f32_16x16x32_bf16 v[60:63], v[20:23], v[190:193], v[32:35]
	v_mfma_f32_16x16x32_bf16 v[32:35], v[152:155], v[186:189], v[56:59]
	v_mfma_f32_16x16x32_bf16 v[56:59], v[156:159], v[190:193], v[32:35]
	v_mfma_f32_16x16x32_bf16 v[32:35], v[16:19], v[194:197], v[44:47]
	v_mfma_f32_16x16x32_bf16 v[8:11], v[16:19], v[160:163], v[76:79]
	v_mfma_f32_16x16x32_bf16 v[44:47], v[20:23], v[198:201], v[32:35]
	v_mfma_f32_16x16x32_bf16 v[32:35], v[152:155], v[194:197], v[40:43]
	v_mfma_f32_16x16x32_bf16 v[16:19], v[16:19], v[202:205], v[28:31]
	v_mfma_f32_16x16x32_bf16 v[8:11], v[20:23], v[164:167], v[8:11]
	v_mfma_f32_16x16x32_bf16 v[12:15], v[152:155], v[160:163], v[72:75]
	v_mfma_f32_16x16x32_bf16 v[40:43], v[156:159], v[198:201], v[32:35]
	v_mfma_f32_16x16x32_bf16 v[16:19], v[20:23], v[206:209], v[16:19]
	v_mfma_f32_16x16x32_bf16 v[20:23], v[152:155], v[202:205], v[24:27]
	v_mfma_f32_16x16x32_bf16 v[12:15], v[156:159], v[164:167], v[12:15]
	v_mfma_f32_16x16x32_bf16 v[20:23], v[156:159], v[206:209], v[20:23]
	s_setprio 0
	s_barrier
	s_add_i32 s42, 0, 0x18000
	v_add_u32_e32 v36, s42, v226
	s_add_i32 s43, 0, 0x1c000
	ds_read_b128 v[24:27], v36
	ds_read_b128 v[28:31], v36 offset:1024
	ds_read_b128 v[32:35], v36 offset:2048
	ds_read_b128 v[72:75], v36 offset:3072
	v_add_u32_e32 v36, s43, v226
	ds_read_b128 v[152:155], v36
	ds_read_b128 v[156:159], v36 offset:1024
	ds_read_b128 v[160:163], v36 offset:2048
	ds_read_b128 v[164:167], v36 offset:3072
	s_add_u32 s36, s74, 0x80000
	s_addc_u32 s37, s75, 0
	s_mov_b32 m0, s77
	v_lshl_add_u64 v[210:211], s[36:37], 0, v[170:171]
	ds_read_b128 v[36:39], v229 offset:32768
	ds_read_b128 v[76:79], v229 offset:33792
	ds_read_b128 v[186:189], v229 offset:34816
	ds_read_b128 v[190:193], v229 offset:35840
	ds_read_b128 v[194:197], v229 offset:36864
	ds_read_b128 v[198:201], v229 offset:37888
	ds_read_b128 v[202:205], v229 offset:38912
	ds_read_b128 v[206:209], v229 offset:39936
	global_load_lds_dwordx4 v[210:211], off
	v_lshl_add_u64 v[210:211], s[36:37], 0, v[174:175]
	s_mov_b32 m0, s78
	s_nop 0
	global_load_lds_dwordx4 v[210:211], off
	s_waitcnt vmcnt(8)
	s_waitcnt lgkmcnt(0)
	s_barrier
	s_setprio 1
	s_waitcnt lgkmcnt(0)
	v_mfma_f32_16x16x32_bf16 v[148:151], v[24:27], v[36:39], v[148:151]
	v_mfma_f32_16x16x32_bf16 v[144:147], v[32:35], v[36:39], v[144:147]
	v_mfma_f32_16x16x32_bf16 v[132:135], v[24:27], v[186:189], v[132:135]
	v_mfma_f32_16x16x32_bf16 v[128:131], v[32:35], v[186:189], v[128:131]
	v_mfma_f32_16x16x32_bf16 v[116:119], v[24:27], v[194:197], v[116:119]
	v_mfma_f32_16x16x32_bf16 v[112:115], v[32:35], v[194:197], v[112:115]
	v_mfma_f32_16x16x32_bf16 v[100:103], v[24:27], v[202:205], v[100:103]
	v_mfma_f32_16x16x32_bf16 v[96:99], v[32:35], v[202:205], v[96:99]
	v_mfma_f32_16x16x32_bf16 v[148:151], v[28:31], v[76:79], v[148:151]
	v_mfma_f32_16x16x32_bf16 v[144:147], v[72:75], v[76:79], v[144:147]
	v_mfma_f32_16x16x32_bf16 v[132:135], v[28:31], v[190:193], v[132:135]
	v_mfma_f32_16x16x32_bf16 v[128:131], v[72:75], v[190:193], v[128:131]
	v_mfma_f32_16x16x32_bf16 v[116:119], v[28:31], v[198:201], v[116:119]
	v_mfma_f32_16x16x32_bf16 v[112:115], v[72:75], v[198:201], v[112:115]
	v_mfma_f32_16x16x32_bf16 v[100:103], v[28:31], v[206:209], v[100:103]
	v_mfma_f32_16x16x32_bf16 v[96:99], v[72:75], v[206:209], v[96:99]
	v_mfma_f32_16x16x32_bf16 v[140:143], v[152:155], v[36:39], v[140:143]
	v_mfma_f32_16x16x32_bf16 v[36:39], v[160:163], v[36:39], v[136:139]
	v_mfma_f32_16x16x32_bf16 v[136:139], v[164:167], v[76:79], v[36:39]
	v_mfma_f32_16x16x32_bf16 v[36:39], v[152:155], v[186:189], v[124:127]
	v_mfma_f32_16x16x32_bf16 v[124:127], v[156:159], v[190:193], v[36:39]
	v_mfma_f32_16x16x32_bf16 v[36:39], v[160:163], v[186:189], v[120:123]
	v_mfma_f32_16x16x32_bf16 v[120:123], v[164:167], v[190:193], v[36:39]
	v_mfma_f32_16x16x32_bf16 v[36:39], v[152:155], v[194:197], v[108:111]
	v_mfma_f32_16x16x32_bf16 v[108:111], v[156:159], v[198:201], v[36:39]
	v_mfma_f32_16x16x32_bf16 v[36:39], v[160:163], v[194:197], v[104:107]
	v_mfma_f32_16x16x32_bf16 v[104:107], v[164:167], v[198:201], v[36:39]
	v_mfma_f32_16x16x32_bf16 v[36:39], v[152:155], v[202:205], v[92:95]
	v_mfma_f32_16x16x32_bf16 v[92:95], v[156:159], v[206:209], v[36:39]
	v_mfma_f32_16x16x32_bf16 v[36:39], v[160:163], v[202:205], v[88:91]
	v_mfma_f32_16x16x32_bf16 v[140:143], v[156:159], v[76:79], v[140:143]
	v_mfma_f32_16x16x32_bf16 v[88:91], v[164:167], v[206:209], v[36:39]
	s_setprio 0
	s_barrier
; #define PG8_STAGE(bufoff, gbase, voff) do { _Pragma("unroll") for (int _i = 0; _i < 2; ++_i) \
;         __builtin_amdgcn_global_load_lds((const unsigned*)((const char*)(gbase) + (voff)[_i]), (LAS unsigned*)(lds + (bufoff) + ldsw + _i * 8192), 16, 0, 0); } while (0)
; #define PG8_LDA(dst, b, h) do { _Pragma("unroll") for (int m = 0; m < 4; ++m) _Pragma("unroll") for (int k = 0; k < 2; ++k) dst[m][k] = *(const LAS bf16x8*)(lds + PG8_SA(b, h) + aoff + m * 2048 + k * 1024); } while (0)
; #define PG8_MMA(ai, bj, At, Bt) do { __builtin_amdgcn_s_setprio(1); _Pragma("unroll") for (int m = 0; m < 4; ++m) _Pragma("unroll") for (int n = 0; n < 2; ++n) _Pragma("unroll") for (int k = 0; k < 2; ++k) \
;         acc[ai][bj][m][n] = __builtin_amdgcn_mfma_f32_16x16x32_bf16(Bt[n][k], At[m][k], acc[ai][bj][m][n], 0, 0, 0); __builtin_amdgcn_s_setprio(0); } while (0)
; #define PG8_WAIT_V(n) asm volatile("s_waitcnt vmcnt(" #n ")" ::: "memory")
; #define PG8_WAIT_L(n) asm volatile("s_waitcnt lgkmcnt(" #n ")" ::: "memory")
; #define PG8_BAR __builtin_amdgcn_s_barrier()
; #define PG8_SCHED __builtin_amdgcn_sched_barrier(0)
; template <class Epi, class Sched>
; __device__ __forceinline__ void gemm_phase(LAS unsigned char* lds, const int K, const Sched& S, const Epi& E) {
;     ...
;         for (int t = 0; t < nt; t += 2) {
;     ...
;             PG8_LDA(At, 1, 1); PG8_STAGE(PG8_SB(1, 0), b3, voffB); PG8_STAGE(PG8_SB(1, 1), b3 + hstep, voffB); PG8_STAGE(PG8_SA(1, 0), a3, voffA);
;             PG8_WAIT_V(8); PG8_WAIT_L(0); PG8_BAR; PG8_MMA(1, 0, At, B0); PG8_MMA(1, 1, At, B1); PG8_BAR; PG8_SCHED;
;         }
	s_add_i32 s36, s42, s45
	s_nop 2
	v_lshl_add_u64 v[36:37], v[218:219], 0, s[30:31]
	s_mov_b32 m0, s36
	ds_read_b128 v[186:189], v229 offset:49152
	ds_read_b128 v[190:193], v229 offset:50176
	ds_read_b128 v[194:197], v229 offset:51200
	ds_read_b128 v[198:201], v229 offset:52224
	ds_read_b128 v[202:205], v229 offset:53248
	ds_read_b128 v[206:209], v229 offset:54272
	ds_read_b128 v[210:213], v229 offset:55296
	ds_read_b128 v[214:217], v229 offset:56320
	global_load_lds_dwordx4 v[36:37], off
	s_add_i32 m0, s36, 0x2000
	s_add_u32 s36, s72, 0x80080
	v_lshl_add_u64 v[36:37], v[220:221], 0, s[30:31]
	s_addc_u32 s37, s73, 0
	s_add_i32 s42, s43, s45
	global_load_lds_dwordx4 v[36:37], off
	v_lshl_add_u64 v[36:37], s[36:37], 0, v[172:173]
	s_mov_b32 m0, s42
	s_nop 0
	global_load_lds_dwordx4 v[36:37], off
	v_lshl_add_u64 v[36:37], s[36:37], 0, v[176:177]
	s_add_i32 m0, s42, 0x2000
	s_nop 0
	global_load_lds_dwordx4 v[36:37], off
	v_lshl_add_u64 v[36:37], v[232:233], 0, s[30:31]
	s_mov_b32 m0, s82
	s_nop 0
	global_load_lds_dwordx4 v[36:37], off
	v_lshl_add_u64 v[36:37], v[234:235], 0, s[30:31]
	s_mov_b32 m0, s83
	s_nop 0
	global_load_lds_dwordx4 v[36:37], off
	s_waitcnt vmcnt(8)
	s_waitcnt lgkmcnt(0)
	s_barrier
	s_setprio 1
	s_waitcnt lgkmcnt(0)
	v_mfma_f32_16x16x32_bf16 v[36:39], v[24:27], v[186:189], v[84:87]
	v_mfma_f32_16x16x32_bf16 v[84:87], v[28:31], v[190:193], v[36:39]
	v_mfma_f32_16x16x32_bf16 v[36:39], v[32:35], v[186:189], v[80:83]
	v_mfma_f32_16x16x32_bf16 v[80:83], v[72:75], v[190:193], v[36:39]
	v_mfma_f32_16x16x32_bf16 v[36:39], v[24:27], v[194:197], v[68:71]
	v_mfma_f32_16x16x32_bf16 v[68:71], v[28:31], v[198:201], v[36:39]
	v_mfma_f32_16x16x32_bf16 v[36:39], v[32:35], v[194:197], v[64:67]
	v_mfma_f32_16x16x32_bf16 v[64:67], v[72:75], v[198:201], v[36:39]
	v_mfma_f32_16x16x32_bf16 v[36:39], v[24:27], v[202:205], v[52:55]
	v_mfma_f32_16x16x32_bf16 v[52:55], v[28:31], v[206:209], v[36:39]
	v_mfma_f32_16x16x32_bf16 v[36:39], v[32:35], v[202:205], v[48:51]
	v_mfma_f32_16x16x32_bf16 v[0:3], v[24:27], v[210:213], v[0:3]
	v_mfma_f32_16x16x32_bf16 v[48:51], v[72:75], v[206:209], v[36:39]
	v_mfma_f32_16x16x32_bf16 v[36:39], v[28:31], v[214:217], v[0:3]
	v_mfma_f32_16x16x32_bf16 v[0:3], v[32:35], v[210:213], v[4:7]
	v_mfma_f32_16x16x32_bf16 v[32:35], v[72:75], v[214:217], v[0:3]
	v_mfma_f32_16x16x32_bf16 v[0:3], v[152:155], v[186:189], v[8:11]
	v_mfma_f32_16x16x32_bf16 v[76:79], v[156:159], v[190:193], v[0:3]
	v_mfma_f32_16x16x32_bf16 v[0:3], v[160:163], v[186:189], v[12:15]
	v_mfma_f32_16x16x32_bf16 v[72:75], v[164:167], v[190:193], v[0:3]
	v_mfma_f32_16x16x32_bf16 v[0:3], v[152:155], v[194:197], v[60:63]
	v_mfma_f32_16x16x32_bf16 v[60:63], v[156:159], v[198:201], v[0:3]
	v_mfma_f32_16x16x32_bf16 v[0:3], v[160:163], v[194:197], v[56:59]
	v_mfma_f32_16x16x32_bf16 v[56:59], v[164:167], v[198:201], v[0:3]
	v_mfma_f32_16x16x32_bf16 v[0:3], v[152:155], v[202:205], v[44:47]
	v_mfma_f32_16x16x32_bf16 v[44:47], v[156:159], v[206:209], v[0:3]
	v_mfma_f32_16x16x32_bf16 v[0:3], v[160:163], v[202:205], v[40:43]
	v_mfma_f32_16x16x32_bf16 v[40:43], v[164:167], v[206:209], v[0:3]
	v_mfma_f32_16x16x32_bf16 v[0:3], v[152:155], v[210:213], v[16:19]
	v_mfma_f32_16x16x32_bf16 v[28:31], v[156:159], v[214:217], v[0:3]
	v_mfma_f32_16x16x32_bf16 v[0:3], v[160:163], v[210:213], v[20:23]
	v_mfma_f32_16x16x32_bf16 v[24:27], v[164:167], v[214:217], v[0:3]
	s_setprio 0
	s_barrier
	s_add_i32 s9, s9, 2
	s_add_u32 s6, s6, 0x100
	s_addc_u32 s7, s7, 0
	s_add_u32 s1, s1, 0x100
	s_addc_u32 s8, s8, 0
	s_cmp_gt_u32 s9, 29
	s_cbranch_scc0 .LBB0_661
	s_and_b64 vcc, exec, s[34:35]
	s_cbranch_vccz .LBB0_664
	s_barrier

; #define PG8_STAGE(bufoff, gbase, voff) do { _Pragma("unroll") for (int _i = 0; _i < 2; ++_i) \
;         __builtin_amdgcn_global_load_lds((const unsigned*)((const char*)(gbase) + (voff)[_i]), (LAS unsigned*)(lds + (bufoff) + ldsw + _i * 8192), 16, 0, 0); } while (0)
; #define PG8_LDA(dst, b, h) do { _Pragma("unroll") for (int m = 0; m < 4; ++m) _Pragma("unroll") for (int k = 0; k < 2; ++k) dst[m][k] = *(const LAS bf16x8*)(lds + PG8_SA(b, h) + aoff + m * 2048 + k * 1024); } while (0)
; #define PG8_LDB(dst, b, h) do { _Pragma("unroll") for (int n = 0; n < 2; ++n) _Pragma("unroll") for (int k = 0; k < 2; ++k) dst[n][k] = *(const LAS bf16x8*)(lds + PG8_SB(b, h) + boff + n * 2048 + k * 1024); } while (0)
; #define PG8_MMA(ai, bj, At, Bt) do { __builtin_amdgcn_s_setprio(1); _Pragma("unroll") for (int m = 0; m < 4; ++m) _Pragma("unroll") for (int n = 0; n < 2; ++n) _Pragma("unroll") for (int k = 0; k < 2; ++k) \
;         acc[ai][bj][m][n] = __builtin_amdgcn_mfma_f32_16x16x32_bf16(Bt[n][k], At[m][k], acc[ai][bj][m][n], 0, 0, 0); __builtin_amdgcn_s_setprio(0); } while (0)
; #define PG8_WAIT_V(n) asm volatile("s_waitcnt vmcnt(" #n ")" ::: "memory")
; #define PG8_WAIT_L(n) asm volatile("s_waitcnt lgkmcnt(" #n ")" ::: "memory")
; #define PG8_BAR __builtin_amdgcn_s_barrier()
; #define PG8_SCHED __builtin_amdgcn_sched_barrier(0)
; template <class Epi, class Sched>
; __device__ __forceinline__ void gemm_phase(LAS unsigned char* lds, const int K, const Sched& S, const Epi& E) {
;     ...
;             PG8_LDB(B0, 0, 0); PG8_LDB(B1, 0, 1); PG8_SCHED; PG8_LDA(At, 0, 0); PG8_STAGE(PG8_SA(1, 1), a1 + hstep, voffA);
;             PG8_WAIT_V(8); PG8_WAIT_L(0); PG8_BAR; PG8_MMA(0, 0, At, B0); PG8_MMA(0, 1, At, B1); PG8_BAR; PG8_SCHED;
;             PG8_LDA(At, 0, 1); PG8_STAGE(PG8_SB(0, 0), b2, voffB); PG8_STAGE(PG8_SB(0, 1), b2 + hstep, voffB); PG8_STAGE(PG8_SA(0, 0), a2, voffA);
;             PG8_WAIT_V(8); PG8_WAIT_L(0); PG8_BAR; PG8_MMA(1, 0, At, B0); PG8_MMA(1, 1, At, B1); PG8_BAR; PG8_SCHED;
.LBB0_1341:
	ds_read_b128 v[140:143], v147
	ds_read_b128 v[152:155], v147 offset:1024
	ds_read_b128 v[156:159], v147 offset:2048
	ds_read_b128 v[160:163], v147 offset:3072
	ds_read_b128 v[164:167], v148
	ds_read_b128 v[168:171], v148 offset:1024
	ds_read_b128 v[172:175], v148 offset:2048
	ds_read_b128 v[176:179], v148 offset:3072
	s_add_u32 s19, s34, 0xfff80080
	s_addc_u32 s36, s35, -1
	s_cmp_eq_u32 s17, 28
	s_cselect_b32 s39, s23, s36
	s_cselect_b32 s38, s22, s19
	s_cselect_b32 s37, s25, s9
	s_cselect_b32 s36, s24, s8
	v_lshl_add_u64 v[212:213], s[34:35], 0, v[136:137]
	s_add_i32 m0, s27, 0xc000
	ds_read_b128 v[180:183], v149
	ds_read_b128 v[184:187], v149 offset:1024
	ds_read_b128 v[188:191], v149 offset:2048
	ds_read_b128 v[192:195], v149 offset:3072
	ds_read_b128 v[196:199], v149 offset:4096
	ds_read_b128 v[200:203], v149 offset:5120
	ds_read_b128 v[204:207], v149 offset:6144
	ds_read_b128 v[208:211], v149 offset:7168
	global_load_lds_dwordx4 v[212:213], off
	v_lshl_add_u64 v[212:213], s[34:35], 0, v[138:139]
	s_add_i32 m0, s27, 0xe000
	s_nop 0
	global_load_lds_dwordx4 v[212:213], off
	s_waitcnt vmcnt(8)
	s_waitcnt lgkmcnt(0)
	s_barrier
	s_setprio 1
	s_waitcnt lgkmcnt(0)
	v_mfma_f32_16x16x32_bf16 v[124:127], v[140:143], v[180:183], v[124:127]
	v_mfma_f32_16x16x32_bf16 v[120:123], v[156:159], v[180:183], v[120:123]
	v_mfma_f32_16x16x32_bf16 v[108:111], v[140:143], v[188:191], v[108:111]
	v_mfma_f32_16x16x32_bf16 v[104:107], v[156:159], v[188:191], v[104:107]
	v_mfma_f32_16x16x32_bf16 v[92:95], v[140:143], v[196:199], v[92:95]
	v_mfma_f32_16x16x32_bf16 v[88:91], v[156:159], v[196:199], v[88:91]
	v_mfma_f32_16x16x32_bf16 v[76:79], v[140:143], v[204:207], v[76:79]
	v_mfma_f32_16x16x32_bf16 v[72:75], v[156:159], v[204:207], v[72:75]
	v_mfma_f32_16x16x32_bf16 v[124:127], v[152:155], v[184:187], v[124:127]
	v_mfma_f32_16x16x32_bf16 v[120:123], v[160:163], v[184:187], v[120:123]
	v_mfma_f32_16x16x32_bf16 v[108:111], v[152:155], v[192:195], v[108:111]
	v_mfma_f32_16x16x32_bf16 v[104:107], v[160:163], v[192:195], v[104:107]
	v_mfma_f32_16x16x32_bf16 v[92:95], v[152:155], v[200:203], v[92:95]
	v_mfma_f32_16x16x32_bf16 v[88:91], v[160:163], v[200:203], v[88:91]
	v_mfma_f32_16x16x32_bf16 v[76:79], v[152:155], v[208:211], v[76:79]
	v_mfma_f32_16x16x32_bf16 v[72:75], v[160:163], v[208:211], v[72:75]
	v_mfma_f32_16x16x32_bf16 v[116:119], v[164:167], v[180:183], v[116:119]
	v_mfma_f32_16x16x32_bf16 v[112:115], v[172:175], v[180:183], v[112:115]
	v_mfma_f32_16x16x32_bf16 v[100:103], v[164:167], v[188:191], v[100:103]
	v_mfma_f32_16x16x32_bf16 v[96:99], v[172:175], v[188:191], v[96:99]
	v_mfma_f32_16x16x32_bf16 v[84:87], v[164:167], v[196:199], v[84:87]
	v_mfma_f32_16x16x32_bf16 v[80:83], v[172:175], v[196:199], v[80:83]
	v_mfma_f32_16x16x32_bf16 v[68:71], v[164:167], v[204:207], v[68:71]
	v_mfma_f32_16x16x32_bf16 v[64:67], v[172:175], v[204:207], v[64:67]
	v_mfma_f32_16x16x32_bf16 v[116:119], v[168:171], v[184:187], v[116:119]
	v_mfma_f32_16x16x32_bf16 v[112:115], v[176:179], v[184:187], v[112:115]
	v_mfma_f32_16x16x32_bf16 v[100:103], v[168:171], v[192:195], v[100:103]
	v_mfma_f32_16x16x32_bf16 v[96:99], v[176:179], v[192:195], v[96:99]
	v_mfma_f32_16x16x32_bf16 v[84:87], v[168:171], v[200:203], v[84:87]
	v_mfma_f32_16x16x32_bf16 v[80:83], v[176:179], v[200:203], v[80:83]
	v_mfma_f32_16x16x32_bf16 v[68:71], v[168:171], v[208:211], v[68:71]
	v_mfma_f32_16x16x32_bf16 v[64:67], v[176:179], v[208:211], v[64:67]
	s_setprio 0
	s_barrier
	s_add_i32 s19, s48, s40
	v_lshl_add_u64 v[212:213], s[36:37], 0, v[130:131]
	s_mov_b32 m0, s19
	ds_read_b128 v[180:183], v149 offset:16384
	ds_read_b128 v[184:187], v149 offset:17408
	ds_read_b128 v[188:191], v149 offset:18432
	ds_read_b128 v[192:195], v149 offset:19456
	ds_read_b128 v[196:199], v149 offset:20480
	ds_read_b128 v[200:203], v149 offset:21504
	ds_read_b128 v[204:207], v149 offset:22528
	ds_read_b128 v[208:211], v149 offset:23552
	global_load_lds_dwordx4 v[212:213], off
	s_add_i32 m0, s19, 0x2000
	s_add_u32 s50, s36, 0x80000
	v_lshl_add_u64 v[214:215], s[36:37], 0, v[134:135]
	s_addc_u32 s51, s37, 0
	s_add_i32 s19, s49, s40
	global_load_lds_dwordx4 v[214:215], off
	v_lshl_add_u64 v[216:217], s[50:51], 0, v[130:131]
	s_mov_b32 m0, s19
	v_lshl_add_u64 v[218:219], s[38:39], 0, v[132:133]
	global_load_lds_dwordx4 v[216:217], off
	v_lshl_add_u64 v[216:217], s[50:51], 0, v[134:135]
	s_add_i32 m0, s19, 0x2000
	s_nop 0
	global_load_lds_dwordx4 v[216:217], off
	v_lshl_add_u64 v[216:217], s[38:39], 0, v[128:129]
	s_mov_b32 m0, s27
	s_nop 0
	global_load_lds_dwordx4 v[216:217], off
	s_mov_b32 m0, s31
	s_nop 0
	global_load_lds_dwordx4 v[218:219], off
	s_waitcnt vmcnt(8)
	s_waitcnt lgkmcnt(0)
	s_barrier
; #define PG8_STAGE(bufoff, gbase, voff) do { _Pragma("unroll") for (int _i = 0; _i < 2; ++_i) \
;         __builtin_amdgcn_global_load_lds((const unsigned*)((const char*)(gbase) + (voff)[_i]), (LAS unsigned*)(lds + (bufoff) + ldsw + _i * 8192), 16, 0, 0); } while (0)
; #define PG8_LDA(dst, b, h) do { _Pragma("unroll") for (int m = 0; m < 4; ++m) _Pragma("unroll") for (int k = 0; k < 2; ++k) dst[m][k] = *(const LAS bf16x8*)(lds + PG8_SA(b, h) + aoff + m * 2048 + k * 1024); } while (0)
; #define PG8_LDB(dst, b, h) do { _Pragma("unroll") for (int n = 0; n < 2; ++n) _Pragma("unroll") for (int k = 0; k < 2; ++k) dst[n][k] = *(const LAS bf16x8*)(lds + PG8_SB(b, h) + boff + n * 2048 + k * 1024); } while (0)
; #define PG8_MMA(ai, bj, At, Bt) do { __builtin_amdgcn_s_setprio(1); _Pragma("unroll") for (int m = 0; m < 4; ++m) _Pragma("unroll") for (int n = 0; n < 2; ++n) _Pragma("unroll") for (int k = 0; k < 2; ++k) \
;         acc[ai][bj][m][n] = __builtin_amdgcn_mfma_f32_16x16x32_bf16(Bt[n][k], At[m][k], acc[ai][bj][m][n], 0, 0, 0); __builtin_amdgcn_s_setprio(0); } while (0)
; #define PG8_WAIT_V(n) asm volatile("s_waitcnt vmcnt(" #n ")" ::: "memory")
; #define PG8_WAIT_L(n) asm volatile("s_waitcnt lgkmcnt(" #n ")" ::: "memory")
; #define PG8_BAR __builtin_amdgcn_s_barrier()
; #define PG8_SCHED __builtin_amdgcn_sched_barrier(0)
; template <class Epi, class Sched>
; __device__ __forceinline__ void gemm_phase(LAS unsigned char* lds, const int K, const Sched& S, const Epi& E) {
;     ...
;             PG8_WAIT_V(8); PG8_WAIT_L(0); PG8_BAR; PG8_MMA(1, 0, At, B0); PG8_MMA(1, 1, At, B1); PG8_BAR; PG8_SCHED;
;             PG8_LDB(B0, 1, 0); PG8_LDB(B1, 1, 1); PG8_SCHED; PG8_LDA(At, 1, 0); PG8_STAGE(PG8_SA(0, 1), a2 + hstep, voffA);
;             PG8_WAIT_V(8); PG8_WAIT_L(0); PG8_BAR; PG8_MMA(0, 0, At, B0); PG8_MMA(0, 1, At, B1); PG8_BAR; PG8_SCHED;
	s_setprio 1
	s_waitcnt lgkmcnt(0)
	v_mfma_f32_16x16x32_bf16 v[60:63], v[140:143], v[180:183], v[60:63]
	v_mfma_f32_16x16x32_bf16 v[56:59], v[156:159], v[180:183], v[56:59]
	v_mfma_f32_16x16x32_bf16 v[44:47], v[140:143], v[188:191], v[44:47]
	v_mfma_f32_16x16x32_bf16 v[40:43], v[156:159], v[188:191], v[40:43]
	v_mfma_f32_16x16x32_bf16 v[28:31], v[140:143], v[196:199], v[28:31]
	v_mfma_f32_16x16x32_bf16 v[24:27], v[156:159], v[196:199], v[24:27]
	v_mfma_f32_16x16x32_bf16 v[12:15], v[140:143], v[204:207], v[12:15]
	v_mfma_f32_16x16x32_bf16 v[8:11], v[156:159], v[204:207], v[8:11]
	v_mfma_f32_16x16x32_bf16 v[60:63], v[152:155], v[184:187], v[60:63]
	v_mfma_f32_16x16x32_bf16 v[56:59], v[160:163], v[184:187], v[56:59]
	v_mfma_f32_16x16x32_bf16 v[44:47], v[152:155], v[192:195], v[44:47]
	v_mfma_f32_16x16x32_bf16 v[40:43], v[160:163], v[192:195], v[40:43]
	v_mfma_f32_16x16x32_bf16 v[28:31], v[152:155], v[200:203], v[28:31]
	v_mfma_f32_16x16x32_bf16 v[24:27], v[160:163], v[200:203], v[24:27]
	v_mfma_f32_16x16x32_bf16 v[12:15], v[152:155], v[208:211], v[12:15]
	v_mfma_f32_16x16x32_bf16 v[8:11], v[160:163], v[208:211], v[8:11]
	v_mfma_f32_16x16x32_bf16 v[52:55], v[164:167], v[180:183], v[52:55]
	v_mfma_f32_16x16x32_bf16 v[48:51], v[172:175], v[180:183], v[48:51]
	v_mfma_f32_16x16x32_bf16 v[36:39], v[164:167], v[188:191], v[36:39]
	v_mfma_f32_16x16x32_bf16 v[32:35], v[172:175], v[188:191], v[32:35]
	v_mfma_f32_16x16x32_bf16 v[20:23], v[164:167], v[196:199], v[20:23]
	v_mfma_f32_16x16x32_bf16 v[16:19], v[172:175], v[196:199], v[16:19]
	v_mfma_f32_16x16x32_bf16 v[4:7], v[164:167], v[204:207], v[4:7]
	v_mfma_f32_16x16x32_bf16 v[0:3], v[172:175], v[204:207], v[0:3]
	v_mfma_f32_16x16x32_bf16 v[52:55], v[168:171], v[184:187], v[52:55]
	v_mfma_f32_16x16x32_bf16 v[48:51], v[176:179], v[184:187], v[48:51]
	v_mfma_f32_16x16x32_bf16 v[36:39], v[168:171], v[192:195], v[36:39]
	v_mfma_f32_16x16x32_bf16 v[32:35], v[176:179], v[192:195], v[32:35]
	v_mfma_f32_16x16x32_bf16 v[20:23], v[168:171], v[200:203], v[20:23]
	v_mfma_f32_16x16x32_bf16 v[16:19], v[176:179], v[200:203], v[16:19]
	v_mfma_f32_16x16x32_bf16 v[4:7], v[168:171], v[208:211], v[4:7]
	v_mfma_f32_16x16x32_bf16 v[0:3], v[176:179], v[208:211], v[0:3]
	s_setprio 0
	s_barrier
	s_add_i32 s19, 0, 0x18000
	v_add_u32_e32 v151, s19, v146
	s_add_i32 s50, 0, 0x1c000
	ds_read_b128 v[140:143], v151
	ds_read_b128 v[152:155], v151 offset:1024
	ds_read_b128 v[156:159], v151 offset:2048
	ds_read_b128 v[160:163], v151 offset:3072
	v_add_u32_e32 v151, s50, v146
	ds_read_b128 v[164:167], v151
	ds_read_b128 v[168:171], v151 offset:1024
	ds_read_b128 v[172:175], v151 offset:2048
	ds_read_b128 v[176:179], v151 offset:3072
	s_add_u32 s38, s38, 0x80000
	s_addc_u32 s39, s39, 0
	s_mov_b32 m0, s41
	v_lshl_add_u64 v[220:221], s[38:39], 0, v[128:129]
	ds_read_b128 v[180:183], v149 offset:32768
	ds_read_b128 v[184:187], v149 offset:33792
	ds_read_b128 v[188:191], v149 offset:34816
	ds_read_b128 v[192:195], v149 offset:35840
	ds_read_b128 v[196:199], v149 offset:36864
	ds_read_b128 v[200:203], v149 offset:37888
	ds_read_b128 v[204:207], v149 offset:38912
	ds_read_b128 v[208:211], v149 offset:39936
	global_load_lds_dwordx4 v[220:221], off
	v_lshl_add_u64 v[220:221], s[38:39], 0, v[132:133]
	s_mov_b32 m0, s42
	s_nop 0
	global_load_lds_dwordx4 v[220:221], off
	s_waitcnt vmcnt(8)
	s_waitcnt lgkmcnt(0)
	s_barrier
	s_setprio 1
	s_waitcnt lgkmcnt(0)
	v_mfma_f32_16x16x32_bf16 v[124:127], v[140:143], v[180:183], v[124:127]
	v_mfma_f32_16x16x32_bf16 v[120:123], v[156:159], v[180:183], v[120:123]
	v_mfma_f32_16x16x32_bf16 v[108:111], v[140:143], v[188:191], v[108:111]
	v_mfma_f32_16x16x32_bf16 v[104:107], v[156:159], v[188:191], v[104:107]
	v_mfma_f32_16x16x32_bf16 v[92:95], v[140:143], v[196:199], v[92:95]
	v_mfma_f32_16x16x32_bf16 v[88:91], v[156:159], v[196:199], v[88:91]
	v_mfma_f32_16x16x32_bf16 v[76:79], v[140:143], v[204:207], v[76:79]
	v_mfma_f32_16x16x32_bf16 v[72:75], v[156:159], v[204:207], v[72:75]
	v_mfma_f32_16x16x32_bf16 v[124:127], v[152:155], v[184:187], v[124:127]
	v_mfma_f32_16x16x32_bf16 v[120:123], v[160:163], v[184:187], v[120:123]
	v_mfma_f32_16x16x32_bf16 v[108:111], v[152:155], v[192:195], v[108:111]
	v_mfma_f32_16x16x32_bf16 v[104:107], v[160:163], v[192:195], v[104:107]
	v_mfma_f32_16x16x32_bf16 v[92:95], v[152:155], v[200:203], v[92:95]
	v_mfma_f32_16x16x32_bf16 v[88:91], v[160:163], v[200:203], v[88:91]
	v_mfma_f32_16x16x32_bf16 v[76:79], v[152:155], v[208:211], v[76:79]
	v_mfma_f32_16x16x32_bf16 v[72:75], v[160:163], v[208:211], v[72:75]
	v_mfma_f32_16x16x32_bf16 v[116:119], v[164:167], v[180:183], v[116:119]
	v_mfma_f32_16x16x32_bf16 v[112:115], v[172:175], v[180:183], v[112:115]
	v_mfma_f32_16x16x32_bf16 v[100:103], v[164:167], v[188:191], v[100:103]
	v_mfma_f32_16x16x32_bf16 v[96:99], v[172:175], v[188:191], v[96:99]
	v_mfma_f32_16x16x32_bf16 v[84:87], v[164:167], v[196:199], v[84:87]
	v_mfma_f32_16x16x32_bf16 v[80:83], v[172:175], v[196:199], v[80:83]
	v_mfma_f32_16x16x32_bf16 v[68:71], v[164:167], v[204:207], v[68:71]
	v_mfma_f32_16x16x32_bf16 v[64:67], v[172:175], v[204:207], v[64:67]
	v_mfma_f32_16x16x32_bf16 v[116:119], v[168:171], v[184:187], v[116:119]
	v_mfma_f32_16x16x32_bf16 v[112:115], v[176:179], v[184:187], v[112:115]
	v_mfma_f32_16x16x32_bf16 v[100:103], v[168:171], v[192:195], v[100:103]
	v_mfma_f32_16x16x32_bf16 v[96:99], v[176:179], v[192:195], v[96:99]
	v_mfma_f32_16x16x32_bf16 v[84:87], v[168:171], v[200:203], v[84:87]
	v_mfma_f32_16x16x32_bf16 v[80:83], v[176:179], v[200:203], v[80:83]
	v_mfma_f32_16x16x32_bf16 v[68:71], v[168:171], v[208:211], v[68:71]
	v_mfma_f32_16x16x32_bf16 v[64:67], v[176:179], v[208:211], v[64:67]
	s_setprio 0
	s_barrier
; #define PG8_STAGE(bufoff, gbase, voff) do { _Pragma("unroll") for (int _i = 0; _i < 2; ++_i) \
;         __builtin_amdgcn_global_load_lds((const unsigned*)((const char*)(gbase) + (voff)[_i]), (LAS unsigned*)(lds + (bufoff) + ldsw + _i * 8192), 16, 0, 0); } while (0)
; #define PG8_LDA(dst, b, h) do { _Pragma("unroll") for (int m = 0; m < 4; ++m) _Pragma("unroll") for (int k = 0; k < 2; ++k) dst[m][k] = *(const LAS bf16x8*)(lds + PG8_SA(b, h) + aoff + m * 2048 + k * 1024); } while (0)
; #define PG8_MMA(ai, bj, At, Bt) do { __builtin_amdgcn_s_setprio(1); _Pragma("unroll") for (int m = 0; m < 4; ++m) _Pragma("unroll") for (int n = 0; n < 2; ++n) _Pragma("unroll") for (int k = 0; k < 2; ++k) \
;         acc[ai][bj][m][n] = __builtin_amdgcn_mfma_f32_16x16x32_bf16(Bt[n][k], At[m][k], acc[ai][bj][m][n], 0, 0, 0); __builtin_amdgcn_s_setprio(0); } while (0)
; #define PG8_WAIT_V(n) asm volatile("s_waitcnt vmcnt(" #n ")" ::: "memory")
; #define PG8_WAIT_L(n) asm volatile("s_waitcnt lgkmcnt(" #n ")" ::: "memory")
; #define PG8_BAR __builtin_amdgcn_s_barrier()
; #define PG8_SCHED __builtin_amdgcn_sched_barrier(0)
; template <class Epi, class Sched>
; __device__ __forceinline__ void gemm_phase(LAS unsigned char* lds, const int K, const Sched& S, const Epi& E) {
;     ...
;         for (int t = 0; t < nt; t += 2) {
;     ...
;             PG8_LDA(At, 1, 1); PG8_STAGE(PG8_SB(1, 0), b3, voffB); PG8_STAGE(PG8_SB(1, 1), b3 + hstep, voffB); PG8_STAGE(PG8_SA(1, 0), a3, voffA);
;             PG8_WAIT_V(8); PG8_WAIT_L(0); PG8_BAR; PG8_MMA(1, 0, At, B0); PG8_MMA(1, 1, At, B1); PG8_BAR; PG8_SCHED;
;         }
	s_add_i32 s19, s19, s40
	v_lshl_add_u64 v[212:213], v[212:213], 0, s[12:13]
	s_mov_b32 m0, s19
	ds_read_b128 v[180:183], v149 offset:49152
	ds_read_b128 v[184:187], v149 offset:50176
	ds_read_b128 v[188:191], v149 offset:51200
	ds_read_b128 v[192:195], v149 offset:52224
	ds_read_b128 v[196:199], v149 offset:53248
	ds_read_b128 v[200:203], v149 offset:54272
	ds_read_b128 v[204:207], v149 offset:55296
	ds_read_b128 v[208:211], v149 offset:56320
	global_load_lds_dwordx4 v[212:213], off
	s_add_i32 m0, s19, 0x2000
	s_add_u32 s36, s36, 0x80080
	v_lshl_add_u64 v[212:213], v[214:215], 0, s[12:13]
	s_addc_u32 s37, s37, 0
	s_add_i32 s19, s50, s40
	global_load_lds_dwordx4 v[212:213], off
	v_lshl_add_u64 v[212:213], s[36:37], 0, v[130:131]
	s_mov_b32 m0, s19
	s_nop 0
	global_load_lds_dwordx4 v[212:213], off
	v_lshl_add_u64 v[212:213], s[36:37], 0, v[134:135]
	s_add_i32 m0, s19, 0x2000
	s_nop 0
	global_load_lds_dwordx4 v[212:213], off
	v_lshl_add_u64 v[212:213], v[216:217], 0, s[12:13]
	s_mov_b32 m0, s46
	s_nop 0
	global_load_lds_dwordx4 v[212:213], off
	v_lshl_add_u64 v[212:213], v[218:219], 0, s[12:13]
	s_mov_b32 m0, s47
	s_nop 0
	global_load_lds_dwordx4 v[212:213], off
	s_waitcnt vmcnt(8)
	s_waitcnt lgkmcnt(0)
	s_barrier
	s_setprio 1
	s_waitcnt lgkmcnt(0)
	v_mfma_f32_16x16x32_bf16 v[60:63], v[140:143], v[180:183], v[60:63]
	v_mfma_f32_16x16x32_bf16 v[56:59], v[156:159], v[180:183], v[56:59]
	v_mfma_f32_16x16x32_bf16 v[44:47], v[140:143], v[188:191], v[44:47]
	v_mfma_f32_16x16x32_bf16 v[40:43], v[156:159], v[188:191], v[40:43]
	v_mfma_f32_16x16x32_bf16 v[28:31], v[140:143], v[196:199], v[28:31]
	v_mfma_f32_16x16x32_bf16 v[24:27], v[156:159], v[196:199], v[24:27]
	v_mfma_f32_16x16x32_bf16 v[12:15], v[140:143], v[204:207], v[12:15]
	v_mfma_f32_16x16x32_bf16 v[8:11], v[156:159], v[204:207], v[8:11]
	v_mfma_f32_16x16x32_bf16 v[60:63], v[152:155], v[184:187], v[60:63]
	v_mfma_f32_16x16x32_bf16 v[56:59], v[160:163], v[184:187], v[56:59]
	v_mfma_f32_16x16x32_bf16 v[44:47], v[152:155], v[192:195], v[44:47]
	v_mfma_f32_16x16x32_bf16 v[40:43], v[160:163], v[192:195], v[40:43]
	v_mfma_f32_16x16x32_bf16 v[28:31], v[152:155], v[200:203], v[28:31]
	v_mfma_f32_16x16x32_bf16 v[24:27], v[160:163], v[200:203], v[24:27]
	v_mfma_f32_16x16x32_bf16 v[12:15], v[152:155], v[208:211], v[12:15]
	v_mfma_f32_16x16x32_bf16 v[8:11], v[160:163], v[208:211], v[8:11]
	v_mfma_f32_16x16x32_bf16 v[52:55], v[164:167], v[180:183], v[52:55]
	v_mfma_f32_16x16x32_bf16 v[48:51], v[172:175], v[180:183], v[48:51]
	v_mfma_f32_16x16x32_bf16 v[36:39], v[164:167], v[188:191], v[36:39]
	v_mfma_f32_16x16x32_bf16 v[32:35], v[172:175], v[188:191], v[32:35]
	v_mfma_f32_16x16x32_bf16 v[20:23], v[164:167], v[196:199], v[20:23]
	v_mfma_f32_16x16x32_bf16 v[16:19], v[172:175], v[196:199], v[16:19]
	v_mfma_f32_16x16x32_bf16 v[4:7], v[164:167], v[204:207], v[4:7]
	v_mfma_f32_16x16x32_bf16 v[0:3], v[172:175], v[204:207], v[0:3]
	v_mfma_f32_16x16x32_bf16 v[52:55], v[168:171], v[184:187], v[52:55]
	v_mfma_f32_16x16x32_bf16 v[48:51], v[176:179], v[184:187], v[48:51]
	v_mfma_f32_16x16x32_bf16 v[36:39], v[168:171], v[192:195], v[36:39]
	v_mfma_f32_16x16x32_bf16 v[32:35], v[176:179], v[192:195], v[32:35]
	v_mfma_f32_16x16x32_bf16 v[20:23], v[168:171], v[200:203], v[20:23]
	v_mfma_f32_16x16x32_bf16 v[16:19], v[176:179], v[200:203], v[16:19]
	v_mfma_f32_16x16x32_bf16 v[4:7], v[168:171], v[208:211], v[4:7]
	v_mfma_f32_16x16x32_bf16 v[0:3], v[176:179], v[208:211], v[0:3]
	s_setprio 0
	s_barrier
	s_add_i32 s17, s17, 2
	s_add_u32 s34, s34, 0x100
	s_addc_u32 s35, s35, 0
	s_add_u32 s8, s8, 0x100
	s_addc_u32 s9, s9, 0
	s_cmp_gt_u32 s17, 29
	s_cbranch_scc0 .LBB0_1341
	s_and_b64 vcc, exec, s[14:15]
	s_cbranch_vccz .LBB0_1344
	s_barrier

; #define PG8_STAGE(bufoff, gbase, voff) do { _Pragma("unroll") for (int _i = 0; _i < 2; ++_i) \
;         __builtin_amdgcn_global_load_lds((const unsigned*)((const char*)(gbase) + (voff)[_i]), (LAS unsigned*)(lds + (bufoff) + ldsw + _i * 8192), 16, 0, 0); } while (0)
; #define PG8_LDA(dst, b, h) do { _Pragma("unroll") for (int m = 0; m < 4; ++m) _Pragma("unroll") for (int k = 0; k < 2; ++k) dst[m][k] = *(const LAS bf16x8*)(lds + PG8_SA(b, h) + aoff + m * 2048 + k * 1024); } while (0)
; #define PG8_LDB(dst, b, h) do { _Pragma("unroll") for (int n = 0; n < 2; ++n) _Pragma("unroll") for (int k = 0; k < 2; ++k) dst[n][k] = *(const LAS bf16x8*)(lds + PG8_SB(b, h) + boff + n * 2048 + k * 1024); } while (0)
; #define PG8_MMA(ai, bj, At, Bt) do { __builtin_amdgcn_s_setprio(1); _Pragma("unroll") for (int m = 0; m < 4; ++m) _Pragma("unroll") for (int n = 0; n < 2; ++n) _Pragma("unroll") for (int k = 0; k < 2; ++k) \
;         acc[ai][bj][m][n] = __builtin_amdgcn_mfma_f32_16x16x32_bf16(Bt[n][k], At[m][k], acc[ai][bj][m][n], 0, 0, 0); __builtin_amdgcn_s_setprio(0); } while (0)
; #define PG8_WAIT_V(n) asm volatile("s_waitcnt vmcnt(" #n ")" ::: "memory")
; #define PG8_WAIT_L(n) asm volatile("s_waitcnt lgkmcnt(" #n ")" ::: "memory")
; #define PG8_BAR __builtin_amdgcn_s_barrier()
; #define PG8_SCHED __builtin_amdgcn_sched_barrier(0)
; template <class Epi, class Sched>
; __device__ __forceinline__ void gemm_phase(LAS unsigned char* lds, const int K, const Sched& S, const Epi& E) {
;     ...
;             PG8_LDB(B0, 0, 0); PG8_LDB(B1, 0, 1); PG8_SCHED; PG8_LDA(At, 0, 0); PG8_STAGE(PG8_SA(1, 1), a1 + hstep, voffA);
;             PG8_WAIT_V(8); PG8_WAIT_L(0); PG8_BAR; PG8_MMA(0, 0, At, B0); PG8_MMA(0, 1, At, B1); PG8_BAR; PG8_SCHED;
;             PG8_LDA(At, 0, 1); PG8_STAGE(PG8_SB(0, 0), b2, voffB); PG8_STAGE(PG8_SB(0, 1), b2 + hstep, voffB); PG8_STAGE(PG8_SA(0, 0), a2, voffA);
;             PG8_WAIT_V(8); PG8_WAIT_L(0); PG8_BAR; PG8_MMA(1, 0, At, B0); PG8_MMA(1, 1, At, B1); PG8_BAR; PG8_SCHED;
.LBB0_1433:
	ds_read_b128 v[140:143], v151
	ds_read_b128 v[144:147], v151 offset:1024
	ds_read_b128 v[156:159], v151 offset:2048
	ds_read_b128 v[160:163], v151 offset:3072
	ds_read_b128 v[164:167], v152
	ds_read_b128 v[168:171], v152 offset:1024
	ds_read_b128 v[172:175], v152 offset:2048
	ds_read_b128 v[176:179], v152 offset:3072
	s_add_u32 s25, s34, 0xfff80080
	s_addc_u32 s36, s35, -1
	s_cmp_eq_u32 s23, 28
	s_cselect_b32 s39, s27, s36
	s_cselect_b32 s38, s26, s25
	s_cselect_b32 s37, s31, s9
	s_cselect_b32 s36, s30, s8
	v_lshl_add_u64 v[212:213], s[34:35], 0, v[136:137]
	s_add_i32 m0, s42, 0xc000
	ds_read_b128 v[180:183], v153
	ds_read_b128 v[184:187], v153 offset:1024
	ds_read_b128 v[188:191], v153 offset:2048
	ds_read_b128 v[192:195], v153 offset:3072
	ds_read_b128 v[196:199], v153 offset:4096
	ds_read_b128 v[200:203], v153 offset:5120
	ds_read_b128 v[204:207], v153 offset:6144
	ds_read_b128 v[208:211], v153 offset:7168
	global_load_lds_dwordx4 v[212:213], off
	v_lshl_add_u64 v[212:213], s[34:35], 0, v[138:139]
	s_add_i32 m0, s42, 0xe000
	s_nop 0
	global_load_lds_dwordx4 v[212:213], off
	s_waitcnt vmcnt(8)
	s_waitcnt lgkmcnt(0)
	s_barrier
	s_setprio 1
	s_waitcnt lgkmcnt(0)
	v_mfma_f32_16x16x32_bf16 v[124:127], v[140:143], v[180:183], v[124:127]
	v_mfma_f32_16x16x32_bf16 v[120:123], v[156:159], v[180:183], v[120:123]
	v_mfma_f32_16x16x32_bf16 v[108:111], v[140:143], v[188:191], v[108:111]
	v_mfma_f32_16x16x32_bf16 v[104:107], v[156:159], v[188:191], v[104:107]
	v_mfma_f32_16x16x32_bf16 v[92:95], v[140:143], v[196:199], v[92:95]
	v_mfma_f32_16x16x32_bf16 v[88:91], v[156:159], v[196:199], v[88:91]
	v_mfma_f32_16x16x32_bf16 v[76:79], v[140:143], v[204:207], v[76:79]
	v_mfma_f32_16x16x32_bf16 v[72:75], v[156:159], v[204:207], v[72:75]
	v_mfma_f32_16x16x32_bf16 v[124:127], v[144:147], v[184:187], v[124:127]
	v_mfma_f32_16x16x32_bf16 v[120:123], v[160:163], v[184:187], v[120:123]
	v_mfma_f32_16x16x32_bf16 v[108:111], v[144:147], v[192:195], v[108:111]
	v_mfma_f32_16x16x32_bf16 v[104:107], v[160:163], v[192:195], v[104:107]
	v_mfma_f32_16x16x32_bf16 v[92:95], v[144:147], v[200:203], v[92:95]
	v_mfma_f32_16x16x32_bf16 v[88:91], v[160:163], v[200:203], v[88:91]
	v_mfma_f32_16x16x32_bf16 v[76:79], v[144:147], v[208:211], v[76:79]
	v_mfma_f32_16x16x32_bf16 v[72:75], v[160:163], v[208:211], v[72:75]
	v_mfma_f32_16x16x32_bf16 v[116:119], v[164:167], v[180:183], v[116:119]
	v_mfma_f32_16x16x32_bf16 v[112:115], v[172:175], v[180:183], v[112:115]
	v_mfma_f32_16x16x32_bf16 v[100:103], v[164:167], v[188:191], v[100:103]
	v_mfma_f32_16x16x32_bf16 v[96:99], v[172:175], v[188:191], v[96:99]
	v_mfma_f32_16x16x32_bf16 v[84:87], v[164:167], v[196:199], v[84:87]
	v_mfma_f32_16x16x32_bf16 v[80:83], v[172:175], v[196:199], v[80:83]
	v_mfma_f32_16x16x32_bf16 v[68:71], v[164:167], v[204:207], v[68:71]
	v_mfma_f32_16x16x32_bf16 v[64:67], v[172:175], v[204:207], v[64:67]
	v_mfma_f32_16x16x32_bf16 v[116:119], v[168:171], v[184:187], v[116:119]
	v_mfma_f32_16x16x32_bf16 v[112:115], v[176:179], v[184:187], v[112:115]
	v_mfma_f32_16x16x32_bf16 v[100:103], v[168:171], v[192:195], v[100:103]
	v_mfma_f32_16x16x32_bf16 v[96:99], v[176:179], v[192:195], v[96:99]
	v_mfma_f32_16x16x32_bf16 v[84:87], v[168:171], v[200:203], v[84:87]
	v_mfma_f32_16x16x32_bf16 v[80:83], v[176:179], v[200:203], v[80:83]
	v_mfma_f32_16x16x32_bf16 v[68:71], v[168:171], v[208:211], v[68:71]
	v_mfma_f32_16x16x32_bf16 v[64:67], v[176:179], v[208:211], v[64:67]
	s_setprio 0
	s_barrier
	s_add_i32 s25, s49, s40
	v_lshl_add_u64 v[212:213], s[36:37], 0, v[132:133]
	s_mov_b32 m0, s25
	ds_read_b128 v[180:183], v153 offset:16384
	ds_read_b128 v[184:187], v153 offset:17408
	ds_read_b128 v[188:191], v153 offset:18432
	ds_read_b128 v[192:195], v153 offset:19456
	ds_read_b128 v[196:199], v153 offset:20480
	ds_read_b128 v[200:203], v153 offset:21504
	ds_read_b128 v[204:207], v153 offset:22528
	ds_read_b128 v[208:211], v153 offset:23552
	global_load_lds_dwordx4 v[212:213], off
	s_add_i32 m0, s25, 0x2000
	s_add_u32 s62, s36, 0x80000
	v_lshl_add_u64 v[214:215], s[36:37], 0, v[128:129]
	s_addc_u32 s63, s37, 0
	s_add_i32 s25, s50, s40
	global_load_lds_dwordx4 v[214:215], off
	v_lshl_add_u64 v[216:217], s[62:63], 0, v[132:133]
	s_mov_b32 m0, s25
	v_lshl_add_u64 v[218:219], s[38:39], 0, v[130:131]
	global_load_lds_dwordx4 v[216:217], off
	v_lshl_add_u64 v[216:217], s[62:63], 0, v[128:129]
	s_add_i32 m0, s25, 0x2000
	s_nop 0
	global_load_lds_dwordx4 v[216:217], off
	v_lshl_add_u64 v[216:217], s[38:39], 0, v[134:135]
	s_mov_b32 m0, s42
	s_nop 0
	global_load_lds_dwordx4 v[216:217], off
	s_mov_b32 m0, s43
	s_nop 0
	global_load_lds_dwordx4 v[218:219], off
	s_waitcnt vmcnt(8)
	s_waitcnt lgkmcnt(0)
	s_barrier
; #define PG8_STAGE(bufoff, gbase, voff) do { _Pragma("unroll") for (int _i = 0; _i < 2; ++_i) \
;         __builtin_amdgcn_global_load_lds((const unsigned*)((const char*)(gbase) + (voff)[_i]), (LAS unsigned*)(lds + (bufoff) + ldsw + _i * 8192), 16, 0, 0); } while (0)
; #define PG8_LDA(dst, b, h) do { _Pragma("unroll") for (int m = 0; m < 4; ++m) _Pragma("unroll") for (int k = 0; k < 2; ++k) dst[m][k] = *(const LAS bf16x8*)(lds + PG8_SA(b, h) + aoff + m * 2048 + k * 1024); } while (0)
; #define PG8_LDB(dst, b, h) do { _Pragma("unroll") for (int n = 0; n < 2; ++n) _Pragma("unroll") for (int k = 0; k < 2; ++k) dst[n][k] = *(const LAS bf16x8*)(lds + PG8_SB(b, h) + boff + n * 2048 + k * 1024); } while (0)
; #define PG8_MMA(ai, bj, At, Bt) do { __builtin_amdgcn_s_setprio(1); _Pragma("unroll") for (int m = 0; m < 4; ++m) _Pragma("unroll") for (int n = 0; n < 2; ++n) _Pragma("unroll") for (int k = 0; k < 2; ++k) \
;         acc[ai][bj][m][n] = __builtin_amdgcn_mfma_f32_16x16x32_bf16(Bt[n][k], At[m][k], acc[ai][bj][m][n], 0, 0, 0); __builtin_amdgcn_s_setprio(0); } while (0)
; #define PG8_WAIT_V(n) asm volatile("s_waitcnt vmcnt(" #n ")" ::: "memory")
; #define PG8_WAIT_L(n) asm volatile("s_waitcnt lgkmcnt(" #n ")" ::: "memory")
; #define PG8_BAR __builtin_amdgcn_s_barrier()
; #define PG8_SCHED __builtin_amdgcn_sched_barrier(0)
; template <class Epi, class Sched>
; __device__ __forceinline__ void gemm_phase(LAS unsigned char* lds, const int K, const Sched& S, const Epi& E) {
;     ...
;             PG8_WAIT_V(8); PG8_WAIT_L(0); PG8_BAR; PG8_MMA(1, 0, At, B0); PG8_MMA(1, 1, At, B1); PG8_BAR; PG8_SCHED;
;             PG8_LDB(B0, 1, 0); PG8_LDB(B1, 1, 1); PG8_SCHED; PG8_LDA(At, 1, 0); PG8_STAGE(PG8_SA(0, 1), a2 + hstep, voffA);
;             PG8_WAIT_V(8); PG8_WAIT_L(0); PG8_BAR; PG8_MMA(0, 0, At, B0); PG8_MMA(0, 1, At, B1); PG8_BAR; PG8_SCHED;
	s_setprio 1
	s_waitcnt lgkmcnt(0)
	v_mfma_f32_16x16x32_bf16 v[60:63], v[140:143], v[180:183], v[60:63]
	v_mfma_f32_16x16x32_bf16 v[56:59], v[156:159], v[180:183], v[56:59]
	v_mfma_f32_16x16x32_bf16 v[44:47], v[140:143], v[188:191], v[44:47]
	v_mfma_f32_16x16x32_bf16 v[40:43], v[156:159], v[188:191], v[40:43]
	v_mfma_f32_16x16x32_bf16 v[28:31], v[140:143], v[196:199], v[28:31]
	v_mfma_f32_16x16x32_bf16 v[24:27], v[156:159], v[196:199], v[24:27]
	v_mfma_f32_16x16x32_bf16 v[12:15], v[140:143], v[204:207], v[12:15]
	v_mfma_f32_16x16x32_bf16 v[8:11], v[156:159], v[204:207], v[8:11]
	v_mfma_f32_16x16x32_bf16 v[60:63], v[144:147], v[184:187], v[60:63]
	v_mfma_f32_16x16x32_bf16 v[56:59], v[160:163], v[184:187], v[56:59]
	v_mfma_f32_16x16x32_bf16 v[44:47], v[144:147], v[192:195], v[44:47]
	v_mfma_f32_16x16x32_bf16 v[40:43], v[160:163], v[192:195], v[40:43]
	v_mfma_f32_16x16x32_bf16 v[28:31], v[144:147], v[200:203], v[28:31]
	v_mfma_f32_16x16x32_bf16 v[24:27], v[160:163], v[200:203], v[24:27]
	v_mfma_f32_16x16x32_bf16 v[12:15], v[144:147], v[208:211], v[12:15]
	v_mfma_f32_16x16x32_bf16 v[8:11], v[160:163], v[208:211], v[8:11]
	v_mfma_f32_16x16x32_bf16 v[52:55], v[164:167], v[180:183], v[52:55]
	v_mfma_f32_16x16x32_bf16 v[48:51], v[172:175], v[180:183], v[48:51]
	v_mfma_f32_16x16x32_bf16 v[36:39], v[164:167], v[188:191], v[36:39]
	v_mfma_f32_16x16x32_bf16 v[32:35], v[172:175], v[188:191], v[32:35]
	v_mfma_f32_16x16x32_bf16 v[20:23], v[164:167], v[196:199], v[20:23]
	v_mfma_f32_16x16x32_bf16 v[16:19], v[172:175], v[196:199], v[16:19]
	v_mfma_f32_16x16x32_bf16 v[4:7], v[164:167], v[204:207], v[4:7]
	v_mfma_f32_16x16x32_bf16 v[0:3], v[172:175], v[204:207], v[0:3]
	v_mfma_f32_16x16x32_bf16 v[52:55], v[168:171], v[184:187], v[52:55]
	v_mfma_f32_16x16x32_bf16 v[48:51], v[176:179], v[184:187], v[48:51]
	v_mfma_f32_16x16x32_bf16 v[36:39], v[168:171], v[192:195], v[36:39]
	v_mfma_f32_16x16x32_bf16 v[32:35], v[176:179], v[192:195], v[32:35]
	v_mfma_f32_16x16x32_bf16 v[20:23], v[168:171], v[200:203], v[20:23]
	v_mfma_f32_16x16x32_bf16 v[16:19], v[176:179], v[200:203], v[16:19]
	v_mfma_f32_16x16x32_bf16 v[4:7], v[168:171], v[208:211], v[4:7]
	v_mfma_f32_16x16x32_bf16 v[0:3], v[176:179], v[208:211], v[0:3]
	s_setprio 0
	s_barrier
	s_add_i32 s25, 0, 0x18000
	v_add_u32_e32 v155, s25, v149
	s_add_i32 s61, 0, 0x1c000
	ds_read_b128 v[140:143], v155
	ds_read_b128 v[144:147], v155 offset:1024
	ds_read_b128 v[156:159], v155 offset:2048
	ds_read_b128 v[160:163], v155 offset:3072
	v_add_u32_e32 v155, s61, v149
	ds_read_b128 v[164:167], v155
	ds_read_b128 v[168:171], v155 offset:1024
	ds_read_b128 v[172:175], v155 offset:2048
	ds_read_b128 v[176:179], v155 offset:3072
	s_add_u32 s38, s38, 0x80000
	s_addc_u32 s39, s39, 0
	s_mov_b32 m0, s44
	v_lshl_add_u64 v[220:221], s[38:39], 0, v[134:135]
	ds_read_b128 v[180:183], v153 offset:32768
	ds_read_b128 v[184:187], v153 offset:33792
	ds_read_b128 v[188:191], v153 offset:34816
	ds_read_b128 v[192:195], v153 offset:35840
	ds_read_b128 v[196:199], v153 offset:36864
	ds_read_b128 v[200:203], v153 offset:37888
	ds_read_b128 v[204:207], v153 offset:38912
	ds_read_b128 v[208:211], v153 offset:39936
	global_load_lds_dwordx4 v[220:221], off
	v_lshl_add_u64 v[220:221], s[38:39], 0, v[130:131]
	s_mov_b32 m0, s45
	s_nop 0
	global_load_lds_dwordx4 v[220:221], off
	s_waitcnt vmcnt(8)
	s_waitcnt lgkmcnt(0)
	s_barrier
	s_setprio 1
	s_waitcnt lgkmcnt(0)
	v_mfma_f32_16x16x32_bf16 v[124:127], v[140:143], v[180:183], v[124:127]
	v_mfma_f32_16x16x32_bf16 v[120:123], v[156:159], v[180:183], v[120:123]
	v_mfma_f32_16x16x32_bf16 v[108:111], v[140:143], v[188:191], v[108:111]
	v_mfma_f32_16x16x32_bf16 v[104:107], v[156:159], v[188:191], v[104:107]
	v_mfma_f32_16x16x32_bf16 v[92:95], v[140:143], v[196:199], v[92:95]
	v_mfma_f32_16x16x32_bf16 v[88:91], v[156:159], v[196:199], v[88:91]
	v_mfma_f32_16x16x32_bf16 v[76:79], v[140:143], v[204:207], v[76:79]
	v_mfma_f32_16x16x32_bf16 v[72:75], v[156:159], v[204:207], v[72:75]
	v_mfma_f32_16x16x32_bf16 v[124:127], v[144:147], v[184:187], v[124:127]
	v_mfma_f32_16x16x32_bf16 v[120:123], v[160:163], v[184:187], v[120:123]
	v_mfma_f32_16x16x32_bf16 v[108:111], v[144:147], v[192:195], v[108:111]
	v_mfma_f32_16x16x32_bf16 v[104:107], v[160:163], v[192:195], v[104:107]
	v_mfma_f32_16x16x32_bf16 v[92:95], v[144:147], v[200:203], v[92:95]
	v_mfma_f32_16x16x32_bf16 v[88:91], v[160:163], v[200:203], v[88:91]
	v_mfma_f32_16x16x32_bf16 v[76:79], v[144:147], v[208:211], v[76:79]
	v_mfma_f32_16x16x32_bf16 v[72:75], v[160:163], v[208:211], v[72:75]
	v_mfma_f32_16x16x32_bf16 v[116:119], v[164:167], v[180:183], v[116:119]
	v_mfma_f32_16x16x32_bf16 v[112:115], v[172:175], v[180:183], v[112:115]
	v_mfma_f32_16x16x32_bf16 v[100:103], v[164:167], v[188:191], v[100:103]
	v_mfma_f32_16x16x32_bf16 v[96:99], v[172:175], v[188:191], v[96:99]
	v_mfma_f32_16x16x32_bf16 v[84:87], v[164:167], v[196:199], v[84:87]
	v_mfma_f32_16x16x32_bf16 v[80:83], v[172:175], v[196:199], v[80:83]
	v_mfma_f32_16x16x32_bf16 v[68:71], v[164:167], v[204:207], v[68:71]
	v_mfma_f32_16x16x32_bf16 v[64:67], v[172:175], v[204:207], v[64:67]
	v_mfma_f32_16x16x32_bf16 v[116:119], v[168:171], v[184:187], v[116:119]
	v_mfma_f32_16x16x32_bf16 v[112:115], v[176:179], v[184:187], v[112:115]
	v_mfma_f32_16x16x32_bf16 v[100:103], v[168:171], v[192:195], v[100:103]
	v_mfma_f32_16x16x32_bf16 v[96:99], v[176:179], v[192:195], v[96:99]
	v_mfma_f32_16x16x32_bf16 v[84:87], v[168:171], v[200:203], v[84:87]
	v_mfma_f32_16x16x32_bf16 v[80:83], v[176:179], v[200:203], v[80:83]
	v_mfma_f32_16x16x32_bf16 v[68:71], v[168:171], v[208:211], v[68:71]
	v_mfma_f32_16x16x32_bf16 v[64:67], v[176:179], v[208:211], v[64:67]
	s_setprio 0
	s_barrier
; #define PG8_STAGE(bufoff, gbase, voff) do { _Pragma("unroll") for (int _i = 0; _i < 2; ++_i) \
;         __builtin_amdgcn_global_load_lds((const unsigned*)((const char*)(gbase) + (voff)[_i]), (LAS unsigned*)(lds + (bufoff) + ldsw + _i * 8192), 16, 0, 0); } while (0)
; #define PG8_LDA(dst, b, h) do { _Pragma("unroll") for (int m = 0; m < 4; ++m) _Pragma("unroll") for (int k = 0; k < 2; ++k) dst[m][k] = *(const LAS bf16x8*)(lds + PG8_SA(b, h) + aoff + m * 2048 + k * 1024); } while (0)
; #define PG8_MMA(ai, bj, At, Bt) do { __builtin_amdgcn_s_setprio(1); _Pragma("unroll") for (int m = 0; m < 4; ++m) _Pragma("unroll") for (int n = 0; n < 2; ++n) _Pragma("unroll") for (int k = 0; k < 2; ++k) \
;         acc[ai][bj][m][n] = __builtin_amdgcn_mfma_f32_16x16x32_bf16(Bt[n][k], At[m][k], acc[ai][bj][m][n], 0, 0, 0); __builtin_amdgcn_s_setprio(0); } while (0)
; #define PG8_WAIT_V(n) asm volatile("s_waitcnt vmcnt(" #n ")" ::: "memory")
; #define PG8_WAIT_L(n) asm volatile("s_waitcnt lgkmcnt(" #n ")" ::: "memory")
; #define PG8_BAR __builtin_amdgcn_s_barrier()
; #define PG8_SCHED __builtin_amdgcn_sched_barrier(0)
; template <class Epi, class Sched>
; __device__ __forceinline__ void gemm_phase(LAS unsigned char* lds, const int K, const Sched& S, const Epi& E) {
;     ...
;         for (int t = 0; t < nt; t += 2) {
;     ...
;             PG8_LDA(At, 1, 1); PG8_STAGE(PG8_SB(1, 0), b3, voffB); PG8_STAGE(PG8_SB(1, 1), b3 + hstep, voffB); PG8_STAGE(PG8_SA(1, 0), a3, voffA);
;             PG8_WAIT_V(8); PG8_WAIT_L(0); PG8_BAR; PG8_MMA(1, 0, At, B0); PG8_MMA(1, 1, At, B1); PG8_BAR; PG8_SCHED;
;         }
	s_add_i32 s25, s25, s40
	v_lshl_add_u64 v[212:213], v[212:213], 0, s[16:17]
	s_mov_b32 m0, s25
	ds_read_b128 v[180:183], v153 offset:49152
	ds_read_b128 v[184:187], v153 offset:50176
	ds_read_b128 v[188:191], v153 offset:51200
	ds_read_b128 v[192:195], v153 offset:52224
	ds_read_b128 v[196:199], v153 offset:53248
	ds_read_b128 v[200:203], v153 offset:54272
	ds_read_b128 v[204:207], v153 offset:55296
	ds_read_b128 v[208:211], v153 offset:56320
	global_load_lds_dwordx4 v[212:213], off
	s_add_i32 m0, s25, 0x2000
	s_add_u32 s36, s36, 0x80080
	v_lshl_add_u64 v[212:213], v[214:215], 0, s[16:17]
	s_addc_u32 s37, s37, 0
	s_add_i32 s25, s61, s40
	global_load_lds_dwordx4 v[212:213], off
	v_lshl_add_u64 v[212:213], s[36:37], 0, v[132:133]
	s_mov_b32 m0, s25
	s_nop 0
	global_load_lds_dwordx4 v[212:213], off
	v_lshl_add_u64 v[212:213], s[36:37], 0, v[128:129]
	s_add_i32 m0, s25, 0x2000
	s_nop 0
	global_load_lds_dwordx4 v[212:213], off
	v_lshl_add_u64 v[212:213], v[216:217], 0, s[16:17]
	s_mov_b32 m0, s47
	s_nop 0
	global_load_lds_dwordx4 v[212:213], off
	v_lshl_add_u64 v[212:213], v[218:219], 0, s[16:17]
	s_mov_b32 m0, s48
	s_nop 0
	global_load_lds_dwordx4 v[212:213], off
	s_waitcnt vmcnt(8)
	s_waitcnt lgkmcnt(0)
	s_barrier
	s_setprio 1
	s_waitcnt lgkmcnt(0)
	v_mfma_f32_16x16x32_bf16 v[60:63], v[140:143], v[180:183], v[60:63]
	v_mfma_f32_16x16x32_bf16 v[56:59], v[156:159], v[180:183], v[56:59]
	v_mfma_f32_16x16x32_bf16 v[44:47], v[140:143], v[188:191], v[44:47]
	v_mfma_f32_16x16x32_bf16 v[40:43], v[156:159], v[188:191], v[40:43]
	v_mfma_f32_16x16x32_bf16 v[28:31], v[140:143], v[196:199], v[28:31]
	v_mfma_f32_16x16x32_bf16 v[24:27], v[156:159], v[196:199], v[24:27]
	v_mfma_f32_16x16x32_bf16 v[12:15], v[140:143], v[204:207], v[12:15]
	v_mfma_f32_16x16x32_bf16 v[8:11], v[156:159], v[204:207], v[8:11]
	v_mfma_f32_16x16x32_bf16 v[60:63], v[144:147], v[184:187], v[60:63]
	v_mfma_f32_16x16x32_bf16 v[56:59], v[160:163], v[184:187], v[56:59]
	v_mfma_f32_16x16x32_bf16 v[44:47], v[144:147], v[192:195], v[44:47]
	v_mfma_f32_16x16x32_bf16 v[40:43], v[160:163], v[192:195], v[40:43]
	v_mfma_f32_16x16x32_bf16 v[28:31], v[144:147], v[200:203], v[28:31]
	v_mfma_f32_16x16x32_bf16 v[24:27], v[160:163], v[200:203], v[24:27]
	v_mfma_f32_16x16x32_bf16 v[12:15], v[144:147], v[208:211], v[12:15]
	v_mfma_f32_16x16x32_bf16 v[8:11], v[160:163], v[208:211], v[8:11]
	v_mfma_f32_16x16x32_bf16 v[52:55], v[164:167], v[180:183], v[52:55]
	v_mfma_f32_16x16x32_bf16 v[48:51], v[172:175], v[180:183], v[48:51]
	v_mfma_f32_16x16x32_bf16 v[36:39], v[164:167], v[188:191], v[36:39]
	v_mfma_f32_16x16x32_bf16 v[32:35], v[172:175], v[188:191], v[32:35]
	v_mfma_f32_16x16x32_bf16 v[20:23], v[164:167], v[196:199], v[20:23]
	v_mfma_f32_16x16x32_bf16 v[16:19], v[172:175], v[196:199], v[16:19]
	v_mfma_f32_16x16x32_bf16 v[4:7], v[164:167], v[204:207], v[4:7]
	v_mfma_f32_16x16x32_bf16 v[0:3], v[172:175], v[204:207], v[0:3]
	v_mfma_f32_16x16x32_bf16 v[52:55], v[168:171], v[184:187], v[52:55]
	v_mfma_f32_16x16x32_bf16 v[48:51], v[176:179], v[184:187], v[48:51]
	v_mfma_f32_16x16x32_bf16 v[36:39], v[168:171], v[192:195], v[36:39]
	v_mfma_f32_16x16x32_bf16 v[32:35], v[176:179], v[192:195], v[32:35]
	v_mfma_f32_16x16x32_bf16 v[20:23], v[168:171], v[200:203], v[20:23]
	v_mfma_f32_16x16x32_bf16 v[16:19], v[176:179], v[200:203], v[16:19]
	v_mfma_f32_16x16x32_bf16 v[4:7], v[168:171], v[208:211], v[4:7]
	v_mfma_f32_16x16x32_bf16 v[0:3], v[176:179], v[208:211], v[0:3]
	s_setprio 0
	s_barrier
	s_add_i32 s23, s23, 2
	s_add_u32 s34, s34, 0x100
	s_addc_u32 s35, s35, 0
	s_add_u32 s8, s8, 0x100
	s_addc_u32 s9, s9, 0
	s_cmp_gt_u32 s23, 29
	s_cbranch_scc0 .LBB0_1433
	s_and_b64 vcc, exec, s[18:19]
	s_cbranch_vccz .LBB0_1436
	s_barrier

; #define PG8_STAGE(bufoff, gbase, voff) do { _Pragma("unroll") for (int _i = 0; _i < 2; ++_i) \
;         __builtin_amdgcn_global_load_lds((const unsigned*)((const char*)(gbase) + (voff)[_i]), (LAS unsigned*)(lds + (bufoff) + ldsw + _i * 8192), 16, 0, 0); } while (0)
; #define PG8_LDA(dst, b, h) do { _Pragma("unroll") for (int m = 0; m < 4; ++m) _Pragma("unroll") for (int k = 0; k < 2; ++k) dst[m][k] = *(const LAS bf16x8*)(lds + PG8_SA(b, h) + aoff + m * 2048 + k * 1024); } while (0)
; #define PG8_LDB(dst, b, h) do { _Pragma("unroll") for (int n = 0; n < 2; ++n) _Pragma("unroll") for (int k = 0; k < 2; ++k) dst[n][k] = *(const LAS bf16x8*)(lds + PG8_SB(b, h) + boff + n * 2048 + k * 1024); } while (0)
; #define PG8_MMA(ai, bj, At, Bt) do { __builtin_amdgcn_s_setprio(1); _Pragma("unroll") for (int m = 0; m < 4; ++m) _Pragma("unroll") for (int n = 0; n < 2; ++n) _Pragma("unroll") for (int k = 0; k < 2; ++k) \
;         acc[ai][bj][m][n] = __builtin_amdgcn_mfma_f32_16x16x32_bf16(Bt[n][k], At[m][k], acc[ai][bj][m][n], 0, 0, 0); __builtin_amdgcn_s_setprio(0); } while (0)
; #define PG8_WAIT_V(n) asm volatile("s_waitcnt vmcnt(" #n ")" ::: "memory")
; #define PG8_WAIT_L(n) asm volatile("s_waitcnt lgkmcnt(" #n ")" ::: "memory")
; #define PG8_BAR __builtin_amdgcn_s_barrier()
; #define PG8_SCHED __builtin_amdgcn_sched_barrier(0)
; template <class Epi, class Sched>
; __device__ __forceinline__ void gemm_phase(LAS unsigned char* lds, const int K, const Sched& S, const Epi& E) {
;     ...
;         for (int t = 0; t < nt; t += 2) {
;             const bool last = (t == nt - 2);
;             const char* a1 = cA + (size_t)(t + 1) * kstep;
;             const char* a2 = last ? nA : cA + (size_t)(t + 2) * kstep; const char* b2 = last ? nB : cB + (size_t)(t + 2) * kstep;
;             const char* a3 = a2 + kstep; const char* b3 = b2 + kstep;
;             PG8_LDB(B0, 0, 0); PG8_LDB(B1, 0, 1); PG8_SCHED; PG8_LDA(At, 0, 0); PG8_STAGE(PG8_SA(1, 1), a1 + hstep, voffA);
;             PG8_WAIT_V(8); PG8_WAIT_L(0); PG8_BAR; PG8_MMA(0, 0, At, B0); PG8_MMA(0, 1, At, B1); PG8_BAR; PG8_SCHED;
;             PG8_LDA(At, 0, 1); PG8_STAGE(PG8_SB(0, 0), b2, voffB); PG8_STAGE(PG8_SB(0, 1), b2 + hstep, voffB); PG8_STAGE(PG8_SA(0, 0), a2, voffA);
;             PG8_WAIT_V(8); PG8_WAIT_L(0); PG8_BAR; PG8_MMA(1, 0, At, B0); PG8_MMA(1, 1, At, B1); PG8_BAR; PG8_SCHED;
.LBB0_1513:
	ds_read_b128 v[140:143], v147
	ds_read_b128 v[152:155], v147 offset:1024
	ds_read_b128 v[156:159], v147 offset:2048
	ds_read_b128 v[160:163], v147 offset:3072
	ds_read_b128 v[164:167], v148
	ds_read_b128 v[168:171], v148 offset:1024
	ds_read_b128 v[172:175], v148 offset:2048
	ds_read_b128 v[176:179], v148 offset:3072
	s_add_u32 s24, s22, 0xffea0080
	s_addc_u32 s25, s23, -1
	s_cmpk_eq_i32 s61, 0x54
	s_cselect_b32 s27, s17, s25
	s_cselect_b32 s26, s16, s24
	s_cselect_b32 s25, s19, s9
	s_cselect_b32 s24, s18, s8
	s_mov_b32 m0, s45
	v_lshl_add_u64 v[212:213], s[22:23], 0, v[136:137]
	ds_read_b128 v[180:183], v149
	ds_read_b128 v[184:187], v149 offset:1024
	ds_read_b128 v[188:191], v149 offset:2048
	ds_read_b128 v[192:195], v149 offset:3072
	ds_read_b128 v[196:199], v149 offset:4096
	ds_read_b128 v[200:203], v149 offset:5120
	ds_read_b128 v[204:207], v149 offset:6144
	ds_read_b128 v[208:211], v149 offset:7168
	global_load_lds_dwordx4 v[212:213], off
	v_lshl_add_u64 v[212:213], s[22:23], 0, v[138:139]
	s_mov_b32 m0, s46
	s_nop 0
	global_load_lds_dwordx4 v[212:213], off
	s_waitcnt vmcnt(8)
	s_waitcnt lgkmcnt(0)
	s_barrier
	s_setprio 1
	s_waitcnt lgkmcnt(0)
	v_mfma_f32_16x16x32_bf16 v[124:127], v[140:143], v[180:183], v[124:127]
	v_mfma_f32_16x16x32_bf16 v[120:123], v[156:159], v[180:183], v[120:123]
	v_mfma_f32_16x16x32_bf16 v[108:111], v[140:143], v[188:191], v[108:111]
	v_mfma_f32_16x16x32_bf16 v[104:107], v[156:159], v[188:191], v[104:107]
	v_mfma_f32_16x16x32_bf16 v[92:95], v[140:143], v[196:199], v[92:95]
	v_mfma_f32_16x16x32_bf16 v[88:91], v[156:159], v[196:199], v[88:91]
	v_mfma_f32_16x16x32_bf16 v[76:79], v[140:143], v[204:207], v[76:79]
	v_mfma_f32_16x16x32_bf16 v[72:75], v[156:159], v[204:207], v[72:75]
	v_mfma_f32_16x16x32_bf16 v[124:127], v[152:155], v[184:187], v[124:127]
	v_mfma_f32_16x16x32_bf16 v[120:123], v[160:163], v[184:187], v[120:123]
	v_mfma_f32_16x16x32_bf16 v[108:111], v[152:155], v[192:195], v[108:111]
	v_mfma_f32_16x16x32_bf16 v[104:107], v[160:163], v[192:195], v[104:107]
	v_mfma_f32_16x16x32_bf16 v[92:95], v[152:155], v[200:203], v[92:95]
	v_mfma_f32_16x16x32_bf16 v[88:91], v[160:163], v[200:203], v[88:91]
	v_mfma_f32_16x16x32_bf16 v[76:79], v[152:155], v[208:211], v[76:79]
	v_mfma_f32_16x16x32_bf16 v[72:75], v[160:163], v[208:211], v[72:75]
	v_mfma_f32_16x16x32_bf16 v[116:119], v[164:167], v[180:183], v[116:119]
	v_mfma_f32_16x16x32_bf16 v[112:115], v[172:175], v[180:183], v[112:115]
	v_mfma_f32_16x16x32_bf16 v[100:103], v[164:167], v[188:191], v[100:103]
	v_mfma_f32_16x16x32_bf16 v[96:99], v[172:175], v[188:191], v[96:99]
	v_mfma_f32_16x16x32_bf16 v[84:87], v[164:167], v[196:199], v[84:87]
	v_mfma_f32_16x16x32_bf16 v[80:83], v[172:175], v[196:199], v[80:83]
	v_mfma_f32_16x16x32_bf16 v[68:71], v[164:167], v[204:207], v[68:71]
	v_mfma_f32_16x16x32_bf16 v[64:67], v[172:175], v[204:207], v[64:67]
	v_mfma_f32_16x16x32_bf16 v[116:119], v[168:171], v[184:187], v[116:119]
	v_mfma_f32_16x16x32_bf16 v[112:115], v[176:179], v[184:187], v[112:115]
	v_mfma_f32_16x16x32_bf16 v[100:103], v[168:171], v[192:195], v[100:103]
	v_mfma_f32_16x16x32_bf16 v[96:99], v[176:179], v[192:195], v[96:99]
	v_mfma_f32_16x16x32_bf16 v[84:87], v[168:171], v[200:203], v[84:87]
	v_mfma_f32_16x16x32_bf16 v[80:83], v[176:179], v[200:203], v[80:83]
	v_mfma_f32_16x16x32_bf16 v[68:71], v[168:171], v[208:211], v[68:71]
	v_mfma_f32_16x16x32_bf16 v[64:67], v[176:179], v[208:211], v[64:67]
	s_setprio 0
	s_barrier
	s_mov_b32 m0, s47
	v_lshl_add_u64 v[212:213], s[24:25], 0, v[130:131]
	s_add_u32 s62, s24, 0x160000
	ds_read_b128 v[180:183], v149 offset:16384
	ds_read_b128 v[184:187], v149 offset:17408
	ds_read_b128 v[188:191], v149 offset:18432
	ds_read_b128 v[192:195], v149 offset:19456
	ds_read_b128 v[196:199], v149 offset:20480
	ds_read_b128 v[200:203], v149 offset:21504
	ds_read_b128 v[204:207], v149 offset:22528
	ds_read_b128 v[208:211], v149 offset:23552
	global_load_lds_dwordx4 v[212:213], off
	v_lshl_add_u64 v[214:215], s[24:25], 0, v[134:135]
	s_mov_b32 m0, s48
	s_addc_u32 s63, s25, 0
	s_add_i32 s64, s44, s34
	global_load_lds_dwordx4 v[214:215], off
	v_lshl_add_u64 v[216:217], s[62:63], 0, v[130:131]
	s_mov_b32 m0, s64
	v_lshl_add_u64 v[218:219], s[26:27], 0, v[132:133]
	global_load_lds_dwordx4 v[216:217], off
	v_lshl_add_u64 v[216:217], s[62:63], 0, v[134:135]
	s_add_i32 m0, s64, 0x2000
	s_nop 0
	global_load_lds_dwordx4 v[216:217], off
	v_lshl_add_u64 v[216:217], s[26:27], 0, v[128:129]
	s_mov_b32 m0, s35
	s_nop 0
	global_load_lds_dwordx4 v[216:217], off
	s_mov_b32 m0, s36
	s_nop 0
	global_load_lds_dwordx4 v[218:219], off
	s_waitcnt vmcnt(8)
	s_waitcnt lgkmcnt(0)
	s_barrier
; #define PG8_STAGE(bufoff, gbase, voff) do { _Pragma("unroll") for (int _i = 0; _i < 2; ++_i) \
;         __builtin_amdgcn_global_load_lds((const unsigned*)((const char*)(gbase) + (voff)[_i]), (LAS unsigned*)(lds + (bufoff) + ldsw + _i * 8192), 16, 0, 0); } while (0)
; #define PG8_LDA(dst, b, h) do { _Pragma("unroll") for (int m = 0; m < 4; ++m) _Pragma("unroll") for (int k = 0; k < 2; ++k) dst[m][k] = *(const LAS bf16x8*)(lds + PG8_SA(b, h) + aoff + m * 2048 + k * 1024); } while (0)
; #define PG8_LDB(dst, b, h) do { _Pragma("unroll") for (int n = 0; n < 2; ++n) _Pragma("unroll") for (int k = 0; k < 2; ++k) dst[n][k] = *(const LAS bf16x8*)(lds + PG8_SB(b, h) + boff + n * 2048 + k * 1024); } while (0)
; #define PG8_MMA(ai, bj, At, Bt) do { __builtin_amdgcn_s_setprio(1); _Pragma("unroll") for (int m = 0; m < 4; ++m) _Pragma("unroll") for (int n = 0; n < 2; ++n) _Pragma("unroll") for (int k = 0; k < 2; ++k) \
;         acc[ai][bj][m][n] = __builtin_amdgcn_mfma_f32_16x16x32_bf16(Bt[n][k], At[m][k], acc[ai][bj][m][n], 0, 0, 0); __builtin_amdgcn_s_setprio(0); } while (0)
; #define PG8_WAIT_V(n) asm volatile("s_waitcnt vmcnt(" #n ")" ::: "memory")
; #define PG8_WAIT_L(n) asm volatile("s_waitcnt lgkmcnt(" #n ")" ::: "memory")
; #define PG8_BAR __builtin_amdgcn_s_barrier()
; #define PG8_SCHED __builtin_amdgcn_sched_barrier(0)
; template <class Epi, class Sched>
; __device__ __forceinline__ void gemm_phase(LAS unsigned char* lds, const int K, const Sched& S, const Epi& E) {
;     ...
;             PG8_WAIT_V(8); PG8_WAIT_L(0); PG8_BAR; PG8_MMA(1, 0, At, B0); PG8_MMA(1, 1, At, B1); PG8_BAR; PG8_SCHED;
;             PG8_LDB(B0, 1, 0); PG8_LDB(B1, 1, 1); PG8_SCHED; PG8_LDA(At, 1, 0); PG8_STAGE(PG8_SA(0, 1), a2 + hstep, voffA);
;             PG8_WAIT_V(8); PG8_WAIT_L(0); PG8_BAR; PG8_MMA(0, 0, At, B0); PG8_MMA(0, 1, At, B1); PG8_BAR; PG8_SCHED;
	s_setprio 1
	s_waitcnt lgkmcnt(0)
	v_mfma_f32_16x16x32_bf16 v[60:63], v[140:143], v[180:183], v[60:63]
	v_mfma_f32_16x16x32_bf16 v[56:59], v[156:159], v[180:183], v[56:59]
	v_mfma_f32_16x16x32_bf16 v[44:47], v[140:143], v[188:191], v[44:47]
	v_mfma_f32_16x16x32_bf16 v[40:43], v[156:159], v[188:191], v[40:43]
	v_mfma_f32_16x16x32_bf16 v[28:31], v[140:143], v[196:199], v[28:31]
	v_mfma_f32_16x16x32_bf16 v[24:27], v[156:159], v[196:199], v[24:27]
	v_mfma_f32_16x16x32_bf16 v[12:15], v[140:143], v[204:207], v[12:15]
	v_mfma_f32_16x16x32_bf16 v[8:11], v[156:159], v[204:207], v[8:11]
	v_mfma_f32_16x16x32_bf16 v[60:63], v[152:155], v[184:187], v[60:63]
	v_mfma_f32_16x16x32_bf16 v[56:59], v[160:163], v[184:187], v[56:59]
	v_mfma_f32_16x16x32_bf16 v[44:47], v[152:155], v[192:195], v[44:47]
	v_mfma_f32_16x16x32_bf16 v[40:43], v[160:163], v[192:195], v[40:43]
	v_mfma_f32_16x16x32_bf16 v[28:31], v[152:155], v[200:203], v[28:31]
	v_mfma_f32_16x16x32_bf16 v[24:27], v[160:163], v[200:203], v[24:27]
	v_mfma_f32_16x16x32_bf16 v[12:15], v[152:155], v[208:211], v[12:15]
	v_mfma_f32_16x16x32_bf16 v[8:11], v[160:163], v[208:211], v[8:11]
	v_mfma_f32_16x16x32_bf16 v[52:55], v[164:167], v[180:183], v[52:55]
	v_mfma_f32_16x16x32_bf16 v[48:51], v[172:175], v[180:183], v[48:51]
	v_mfma_f32_16x16x32_bf16 v[36:39], v[164:167], v[188:191], v[36:39]
	v_mfma_f32_16x16x32_bf16 v[32:35], v[172:175], v[188:191], v[32:35]
	v_mfma_f32_16x16x32_bf16 v[20:23], v[164:167], v[196:199], v[20:23]
	v_mfma_f32_16x16x32_bf16 v[16:19], v[172:175], v[196:199], v[16:19]
	v_mfma_f32_16x16x32_bf16 v[4:7], v[164:167], v[204:207], v[4:7]
	v_mfma_f32_16x16x32_bf16 v[0:3], v[172:175], v[204:207], v[0:3]
	v_mfma_f32_16x16x32_bf16 v[52:55], v[168:171], v[184:187], v[52:55]
	v_mfma_f32_16x16x32_bf16 v[48:51], v[176:179], v[184:187], v[48:51]
	v_mfma_f32_16x16x32_bf16 v[36:39], v[168:171], v[192:195], v[36:39]
	v_mfma_f32_16x16x32_bf16 v[32:35], v[176:179], v[192:195], v[32:35]
	v_mfma_f32_16x16x32_bf16 v[20:23], v[168:171], v[200:203], v[20:23]
	v_mfma_f32_16x16x32_bf16 v[16:19], v[176:179], v[200:203], v[16:19]
	v_mfma_f32_16x16x32_bf16 v[4:7], v[168:171], v[208:211], v[4:7]
	v_mfma_f32_16x16x32_bf16 v[0:3], v[176:179], v[208:211], v[0:3]
	s_setprio 0
	s_barrier
	s_add_i32 s62, 0, 0x18000
	v_add_u32_e32 v151, s62, v146
	s_add_i32 s63, 0, 0x1c000
	ds_read_b128 v[140:143], v151
	ds_read_b128 v[152:155], v151 offset:1024
	ds_read_b128 v[156:159], v151 offset:2048
	ds_read_b128 v[160:163], v151 offset:3072
	v_add_u32_e32 v151, s63, v146
	ds_read_b128 v[164:167], v151
	ds_read_b128 v[168:171], v151 offset:1024
	ds_read_b128 v[172:175], v151 offset:2048
	ds_read_b128 v[176:179], v151 offset:3072
	s_add_u32 s26, s26, 0x160000
	s_addc_u32 s27, s27, 0
	s_mov_b32 m0, s37
	v_lshl_add_u64 v[220:221], s[26:27], 0, v[128:129]
	ds_read_b128 v[180:183], v149 offset:32768
	ds_read_b128 v[184:187], v149 offset:33792
	ds_read_b128 v[188:191], v149 offset:34816
	ds_read_b128 v[192:195], v149 offset:35840
	ds_read_b128 v[196:199], v149 offset:36864
	ds_read_b128 v[200:203], v149 offset:37888
	ds_read_b128 v[204:207], v149 offset:38912
	ds_read_b128 v[208:211], v149 offset:39936
	global_load_lds_dwordx4 v[220:221], off
	v_lshl_add_u64 v[220:221], s[26:27], 0, v[132:133]
	s_mov_b32 m0, s38
	s_nop 0
	global_load_lds_dwordx4 v[220:221], off
	s_waitcnt vmcnt(8)
	s_waitcnt lgkmcnt(0)
	s_barrier
	s_setprio 1
	s_waitcnt lgkmcnt(0)
	v_mfma_f32_16x16x32_bf16 v[124:127], v[140:143], v[180:183], v[124:127]
	v_mfma_f32_16x16x32_bf16 v[120:123], v[156:159], v[180:183], v[120:123]
	v_mfma_f32_16x16x32_bf16 v[108:111], v[140:143], v[188:191], v[108:111]
	v_mfma_f32_16x16x32_bf16 v[104:107], v[156:159], v[188:191], v[104:107]
	v_mfma_f32_16x16x32_bf16 v[92:95], v[140:143], v[196:199], v[92:95]
	v_mfma_f32_16x16x32_bf16 v[88:91], v[156:159], v[196:199], v[88:91]
	v_mfma_f32_16x16x32_bf16 v[76:79], v[140:143], v[204:207], v[76:79]
	v_mfma_f32_16x16x32_bf16 v[72:75], v[156:159], v[204:207], v[72:75]
	v_mfma_f32_16x16x32_bf16 v[124:127], v[152:155], v[184:187], v[124:127]
	v_mfma_f32_16x16x32_bf16 v[120:123], v[160:163], v[184:187], v[120:123]
	v_mfma_f32_16x16x32_bf16 v[108:111], v[152:155], v[192:195], v[108:111]
	v_mfma_f32_16x16x32_bf16 v[104:107], v[160:163], v[192:195], v[104:107]
	v_mfma_f32_16x16x32_bf16 v[92:95], v[152:155], v[200:203], v[92:95]
	v_mfma_f32_16x16x32_bf16 v[88:91], v[160:163], v[200:203], v[88:91]
	v_mfma_f32_16x16x32_bf16 v[76:79], v[152:155], v[208:211], v[76:79]
	v_mfma_f32_16x16x32_bf16 v[72:75], v[160:163], v[208:211], v[72:75]
	v_mfma_f32_16x16x32_bf16 v[116:119], v[164:167], v[180:183], v[116:119]
	v_mfma_f32_16x16x32_bf16 v[112:115], v[172:175], v[180:183], v[112:115]
	v_mfma_f32_16x16x32_bf16 v[100:103], v[164:167], v[188:191], v[100:103]
	v_mfma_f32_16x16x32_bf16 v[96:99], v[172:175], v[188:191], v[96:99]
	v_mfma_f32_16x16x32_bf16 v[84:87], v[164:167], v[196:199], v[84:87]
	v_mfma_f32_16x16x32_bf16 v[80:83], v[172:175], v[196:199], v[80:83]
	v_mfma_f32_16x16x32_bf16 v[68:71], v[164:167], v[204:207], v[68:71]
	v_mfma_f32_16x16x32_bf16 v[64:67], v[172:175], v[204:207], v[64:67]
	v_mfma_f32_16x16x32_bf16 v[116:119], v[168:171], v[184:187], v[116:119]
	v_mfma_f32_16x16x32_bf16 v[112:115], v[176:179], v[184:187], v[112:115]
	v_mfma_f32_16x16x32_bf16 v[100:103], v[168:171], v[192:195], v[100:103]
	v_mfma_f32_16x16x32_bf16 v[96:99], v[176:179], v[192:195], v[96:99]
	v_mfma_f32_16x16x32_bf16 v[84:87], v[168:171], v[200:203], v[84:87]
	v_mfma_f32_16x16x32_bf16 v[80:83], v[176:179], v[200:203], v[80:83]
	v_mfma_f32_16x16x32_bf16 v[68:71], v[168:171], v[208:211], v[68:71]
	v_mfma_f32_16x16x32_bf16 v[64:67], v[176:179], v[208:211], v[64:67]
	s_setprio 0
	s_barrier
; #define PG8_STAGE(bufoff, gbase, voff) do { _Pragma("unroll") for (int _i = 0; _i < 2; ++_i) \
;         __builtin_amdgcn_global_load_lds((const unsigned*)((const char*)(gbase) + (voff)[_i]), (LAS unsigned*)(lds + (bufoff) + ldsw + _i * 8192), 16, 0, 0); } while (0)
; #define PG8_LDA(dst, b, h) do { _Pragma("unroll") for (int m = 0; m < 4; ++m) _Pragma("unroll") for (int k = 0; k < 2; ++k) dst[m][k] = *(const LAS bf16x8*)(lds + PG8_SA(b, h) + aoff + m * 2048 + k * 1024); } while (0)
; #define PG8_MMA(ai, bj, At, Bt) do { __builtin_amdgcn_s_setprio(1); _Pragma("unroll") for (int m = 0; m < 4; ++m) _Pragma("unroll") for (int n = 0; n < 2; ++n) _Pragma("unroll") for (int k = 0; k < 2; ++k) \
;         acc[ai][bj][m][n] = __builtin_amdgcn_mfma_f32_16x16x32_bf16(Bt[n][k], At[m][k], acc[ai][bj][m][n], 0, 0, 0); __builtin_amdgcn_s_setprio(0); } while (0)
; #define PG8_WAIT_V(n) asm volatile("s_waitcnt vmcnt(" #n ")" ::: "memory")
; #define PG8_WAIT_L(n) asm volatile("s_waitcnt lgkmcnt(" #n ")" ::: "memory")
; #define PG8_BAR __builtin_amdgcn_s_barrier()
; #define PG8_SCHED __builtin_amdgcn_sched_barrier(0)
; template <class Epi, class Sched>
; __device__ __forceinline__ void gemm_phase(LAS unsigned char* lds, const int K, const Sched& S, const Epi& E) {
;     ...
;             PG8_LDA(At, 1, 1); PG8_STAGE(PG8_SB(1, 0), b3, voffB); PG8_STAGE(PG8_SB(1, 1), b3 + hstep, voffB); PG8_STAGE(PG8_SA(1, 0), a3, voffA);
;             PG8_WAIT_V(8); PG8_WAIT_L(0); PG8_BAR; PG8_MMA(1, 0, At, B0); PG8_MMA(1, 1, At, B1); PG8_BAR; PG8_SCHED;
;         }
;         if (wr == 0) PG8_BAR;
	s_add_i32 s26, s62, s34
	v_lshl_add_u64 v[212:213], v[212:213], 0, s[12:13]
	s_mov_b32 m0, s26
	ds_read_b128 v[180:183], v149 offset:49152
	ds_read_b128 v[184:187], v149 offset:50176
	ds_read_b128 v[188:191], v149 offset:51200
	ds_read_b128 v[192:195], v149 offset:52224
	ds_read_b128 v[196:199], v149 offset:53248
	ds_read_b128 v[200:203], v149 offset:54272
	ds_read_b128 v[204:207], v149 offset:55296
	ds_read_b128 v[208:211], v149 offset:56320
	global_load_lds_dwordx4 v[212:213], off
	s_add_i32 m0, s26, 0x2000
	s_add_u32 s24, s24, 0x160080
	v_lshl_add_u64 v[212:213], v[214:215], 0, s[12:13]
	s_addc_u32 s25, s25, 0
	s_add_i32 s26, s63, s34
	global_load_lds_dwordx4 v[212:213], off
	v_lshl_add_u64 v[212:213], s[24:25], 0, v[130:131]
	s_mov_b32 m0, s26
	s_nop 0
	global_load_lds_dwordx4 v[212:213], off
	v_lshl_add_u64 v[212:213], s[24:25], 0, v[134:135]
	s_add_i32 m0, s26, 0x2000
	s_nop 0
	global_load_lds_dwordx4 v[212:213], off
	v_lshl_add_u64 v[212:213], v[216:217], 0, s[12:13]
	s_mov_b32 m0, s42
	s_nop 0
	global_load_lds_dwordx4 v[212:213], off
	v_lshl_add_u64 v[212:213], v[218:219], 0, s[12:13]
	s_mov_b32 m0, s43
	s_nop 0
	global_load_lds_dwordx4 v[212:213], off
	s_waitcnt vmcnt(8)
	s_waitcnt lgkmcnt(0)
	s_barrier
	s_setprio 1
	s_waitcnt lgkmcnt(0)
	v_mfma_f32_16x16x32_bf16 v[60:63], v[140:143], v[180:183], v[60:63]
	v_mfma_f32_16x16x32_bf16 v[56:59], v[156:159], v[180:183], v[56:59]
	v_mfma_f32_16x16x32_bf16 v[44:47], v[140:143], v[188:191], v[44:47]
	v_mfma_f32_16x16x32_bf16 v[40:43], v[156:159], v[188:191], v[40:43]
	v_mfma_f32_16x16x32_bf16 v[28:31], v[140:143], v[196:199], v[28:31]
	v_mfma_f32_16x16x32_bf16 v[24:27], v[156:159], v[196:199], v[24:27]
	v_mfma_f32_16x16x32_bf16 v[12:15], v[140:143], v[204:207], v[12:15]
	v_mfma_f32_16x16x32_bf16 v[8:11], v[156:159], v[204:207], v[8:11]
	v_mfma_f32_16x16x32_bf16 v[60:63], v[152:155], v[184:187], v[60:63]
	v_mfma_f32_16x16x32_bf16 v[56:59], v[160:163], v[184:187], v[56:59]
	v_mfma_f32_16x16x32_bf16 v[44:47], v[152:155], v[192:195], v[44:47]
	v_mfma_f32_16x16x32_bf16 v[40:43], v[160:163], v[192:195], v[40:43]
	v_mfma_f32_16x16x32_bf16 v[28:31], v[152:155], v[200:203], v[28:31]
	v_mfma_f32_16x16x32_bf16 v[24:27], v[160:163], v[200:203], v[24:27]
	v_mfma_f32_16x16x32_bf16 v[12:15], v[152:155], v[208:211], v[12:15]
	v_mfma_f32_16x16x32_bf16 v[8:11], v[160:163], v[208:211], v[8:11]
	v_mfma_f32_16x16x32_bf16 v[52:55], v[164:167], v[180:183], v[52:55]
	v_mfma_f32_16x16x32_bf16 v[48:51], v[172:175], v[180:183], v[48:51]
	v_mfma_f32_16x16x32_bf16 v[36:39], v[164:167], v[188:191], v[36:39]
	v_mfma_f32_16x16x32_bf16 v[32:35], v[172:175], v[188:191], v[32:35]
	v_mfma_f32_16x16x32_bf16 v[20:23], v[164:167], v[196:199], v[20:23]
	v_mfma_f32_16x16x32_bf16 v[16:19], v[172:175], v[196:199], v[16:19]
	v_mfma_f32_16x16x32_bf16 v[4:7], v[164:167], v[204:207], v[4:7]
	v_mfma_f32_16x16x32_bf16 v[0:3], v[172:175], v[204:207], v[0:3]
	v_mfma_f32_16x16x32_bf16 v[52:55], v[168:171], v[184:187], v[52:55]
	v_mfma_f32_16x16x32_bf16 v[48:51], v[176:179], v[184:187], v[48:51]
	v_mfma_f32_16x16x32_bf16 v[36:39], v[168:171], v[192:195], v[36:39]
	v_mfma_f32_16x16x32_bf16 v[32:35], v[176:179], v[192:195], v[32:35]
	v_mfma_f32_16x16x32_bf16 v[20:23], v[168:171], v[200:203], v[20:23]
	v_mfma_f32_16x16x32_bf16 v[16:19], v[176:179], v[200:203], v[16:19]
	v_mfma_f32_16x16x32_bf16 v[4:7], v[168:171], v[208:211], v[4:7]
	v_mfma_f32_16x16x32_bf16 v[0:3], v[176:179], v[208:211], v[0:3]
	s_setprio 0
	s_barrier
	s_add_i32 s61, s61, 2
	s_add_u32 s22, s22, 0x100
	s_addc_u32 s23, s23, 0
	s_add_u32 s8, s8, 0x100
	s_addc_u32 s9, s9, 0
	s_cmpk_gt_u32 s61, 0x55
	s_cbranch_scc0 .LBB0_1513
	s_and_b64 vcc, exec, s[14:15]
	s_cbranch_vccz .LBB0_1516
	s_barrier
